# MLA row sums: aligned pairs of scalar adds fused into v_pk_add_f32 (58 pairs)
# baseline (speedup 1.0000x reference)
.Lmla_early_skip3:
	v_add_u32_e32 v173, s67, v173
	v_add_u32_e32 v197, s67, v197
	v_add_u32_e32 v193, s67, v193
	v_add_u32_e32 v195, s67, v195
	v_add_u32_e32 v192, s67, v192
	v_add_u32_e32 v198, s67, v198
	v_add_u32_e32 v194, s67, v194
	v_add_u32_e32 v196, s67, v196
	s_sub_i32 s67, 0, s67
	s_xor_b32 s66, s66, 0x8000
	v_exp_f32_e32 v80, v48
	v_exp_f32_e32 v81, v49
	v_exp_f32_e32 v84, v56
	v_exp_f32_e32 v82, v50
	v_exp_f32_e32 v83, v51
	v_exp_f32_e32 v85, v52
	v_exp_f32_e32 v86, v53
	v_exp_f32_e32 v87, v54
	v_exp_f32_e32 v88, v55
	ds_read_b128 v[52:55], v173 offset:53248
	ds_read_b128 v[48:51], v173 offset:49152
	ds_read_b128 v[56:59], v197 offset:49152
	ds_read_b128 v[60:63], v197 offset:53248
	ds_read_b128 v[64:67], v193 offset:49152
	ds_read_b128 v[68:71], v193 offset:53248
	ds_read_b128 v[72:75], v195 offset:49152
	ds_read_b128 v[76:79], v195 offset:53248
	v_pk_add_f32 v[32:33], v[32:33], v[80:81]
	v_cvt_pk_bf16_f32 v80, v80, v81
	v_pk_add_f32 v[34:35], v[34:35], v[82:83]
	v_cvt_pk_bf16_f32 v81, v82, v83
	v_add_f32_e32 v32, v32, v85
	v_add_f32_e32 v33, v33, v86
	v_cvt_pk_bf16_f32 v82, v85, v86
	v_add_f32_e32 v34, v34, v87
	v_add_f32_e32 v35, v35, v88
	v_cvt_pk_bf16_f32 v83, v87, v88
	s_waitcnt lgkmcnt(7)
	s_nop 0
	v_mfma_f32_32x32x16_bf16 v[16:31], v[52:55], v[80:83], v[16:31]
	s_waitcnt lgkmcnt(6)
	v_mfma_f32_32x32x16_bf16 v[0:15], v[48:51], v[80:83], v[0:15]
	v_cvt_pk_bf16_f32 v48, v84, v84
	v_mov_b32_e32 v49, v48
	v_mov_b32_e32 v50, v48
	v_mov_b32_e32 v51, v48
	s_waitcnt lgkmcnt(4)
	s_nop 0
	v_mfma_f32_32x32x16_bf16 v[16:31], v[60:63], v[48:51], v[16:31]
	s_waitcnt lgkmcnt(2)
	v_mfma_f32_32x32x16_bf16 v[16:31], v[68:71], v[48:51], v[16:31]
	s_waitcnt lgkmcnt(0)
	v_mfma_f32_32x32x16_bf16 v[16:31], v[76:79], v[48:51], v[16:31]
	v_mfma_f32_32x32x16_bf16 v[0:15], v[56:59], v[48:51], v[0:15]
	v_mfma_f32_32x32x16_bf16 v[0:15], v[64:67], v[48:51], v[0:15]
	v_mfma_f32_32x32x16_bf16 v[0:15], v[72:75], v[48:51], v[0:15]
	s_nop 11
	v_add_f32_e32 v32, v32, v33
	v_add_f32_e32 v34, v34, v35
	v_add_f32_e32 v32, v32, v34
	ds_bpermute_b32 v33, v218, v32
	s_lshl_b32 s48, s59, 1
	v_mov_b32_e32 v169, v149
	s_waitcnt lgkmcnt(0)
	s_barrier
	v_add_f32_e32 v32, v32, v33
	v_div_scale_f32 v33, s[6:7], v32, v32, 1.0
	v_rcp_f32_e32 v34, v33
	v_div_scale_f32 v35, vcc, 1.0, v32, 1.0
	v_fma_f32 v36, -v33, v34, 1.0
	v_fmac_f32_e32 v34, v36, v34
	v_mul_f32_e32 v36, v35, v34
	v_fma_f32 v37, -v33, v36, v35
	v_fmac_f32_e32 v36, v37, v34
	v_fma_f32 v33, -v33, v36, v35
	v_div_fmas_f32 v33, v33, v34, v36
	v_div_fixup_f32 v32, v33, v32, 1.0
	v_lshlrev_b64 v[34:35], 10, v[170:171]
	v_lshl_add_u64 v[34:35], s[34:35], 0, v[34:35]
	v_pk_mul_f32 v[0:1], v[0:1], v[32:33] op_sel_hi:[1,0]
	v_pk_mul_f32 v[2:3], v[2:3], v[32:33] op_sel_hi:[1,0]
	v_lshl_add_u64 v[34:35], v[34:35], 0, s[48:49]
	v_cvt_pk_bf16_f32 v0, v0, v1
	v_cvt_pk_bf16_f32 v1, v2, v3
	v_pk_mul_f32 v[2:3], v[16:17], v[32:33] op_sel_hi:[1,0]
	v_pk_mul_f32 v[16:17], v[18:19], v[32:33] op_sel_hi:[1,0]
	v_lshl_add_u64 v[34:35], v[34:35], 0, v[168:169]
	v_cvt_pk_bf16_f32 v2, v2, v3
	v_cvt_pk_bf16_f32 v3, v16, v17
	global_store_dwordx2 v[34:35], v[0:1], off
	global_store_dwordx2 v[34:35], v[2:3], off offset:64
	v_pk_mul_f32 v[0:1], v[4:5], v[32:33] op_sel_hi:[1,0]
	v_pk_mul_f32 v[2:3], v[6:7], v[32:33] op_sel_hi:[1,0]
	v_cvt_pk_bf16_f32 v0, v0, v1
	v_cvt_pk_bf16_f32 v1, v2, v3
	v_pk_mul_f32 v[2:3], v[20:21], v[32:33] op_sel_hi:[1,0]
	v_pk_mul_f32 v[4:5], v[22:23], v[32:33] op_sel_hi:[1,0]
	v_cvt_pk_bf16_f32 v2, v2, v3
	v_cvt_pk_bf16_f32 v3, v4, v5
	global_store_dwordx2 v[34:35], v[0:1], off offset:16
	global_store_dwordx2 v[34:35], v[2:3], off offset:80
	v_pk_mul_f32 v[0:1], v[8:9], v[32:33] op_sel_hi:[1,0]
	v_pk_mul_f32 v[2:3], v[10:11], v[32:33] op_sel_hi:[1,0]
	v_cvt_pk_bf16_f32 v0, v0, v1
	v_cvt_pk_bf16_f32 v1, v2, v3
	v_pk_mul_f32 v[2:3], v[24:25], v[32:33] op_sel_hi:[1,0]
	v_pk_mul_f32 v[4:5], v[26:27], v[32:33] op_sel_hi:[1,0]
	v_cvt_pk_bf16_f32 v2, v2, v3
	v_cvt_pk_bf16_f32 v3, v4, v5
	global_store_dwordx2 v[34:35], v[0:1], off offset:32
	global_store_dwordx2 v[34:35], v[2:3], off offset:96
	v_pk_mul_f32 v[0:1], v[12:13], v[32:33] op_sel_hi:[1,0]
	v_pk_mul_f32 v[2:3], v[14:15], v[32:33] op_sel_hi:[1,0]
	v_cvt_pk_bf16_f32 v0, v0, v1
	v_cvt_pk_bf16_f32 v1, v2, v3
	v_pk_mul_f32 v[2:3], v[28:29], v[32:33] op_sel_hi:[1,0]
	v_pk_mul_f32 v[4:5], v[30:31], v[32:33] op_sel_hi:[1,0]
	s_add_i32 s58, s58, s82
	v_cvt_pk_bf16_f32 v2, v2, v3
	v_cvt_pk_bf16_f32 v3, v4, v5
	s_cmpk_gt_i32 s58, 0x3ff
	global_store_dwordx2 v[34:35], v[0:1], off offset:48
	global_store_dwordx2 v[34:35], v[2:3], off offset:112
	s_cbranch_scc1 .LBB0_1225

.LBB0_1193:
	s_mov_b64 s[14:15], 0x3600180
	s_add_i32 s17, s16, 0x12000
	v_lshl_add_u64 v[80:81], v[188:189], 0, s[14:15]
	s_add_i32 m0, s17, s66
	v_exp_f32_e32 v150, v64
	global_load_lds_dwordx4 v[80:81], off
	ds_read_b128 v[80:83], v199 offset:12288
	ds_read_b128 v[84:87], v199 offset:18432
	ds_read_b128 v[154:157], v200 offset:12288
	ds_read_b128 v[202:205], v200 offset:18432
	ds_read_b128 v[212:215], v199 offset:12352
	ds_read_b128 v[220:223], v199 offset:18496
	ds_read_b128 v[224:227], v200 offset:12352
	ds_read_b128 v[228:231], v200 offset:18496
	ds_read_b128 v[232:235], v199 offset:12416
	ds_read_b128 v[236:239], v199 offset:18560
	ds_read_b128 v[240:243], v200 offset:12416
	ds_read_b128 v[244:247], v200 offset:18560
	s_waitcnt lgkmcnt(0)
	v_mfma_f32_32x32x16_bf16 v[96:111], v[80:83], v[136:139], 0
	v_exp_f32_e32 v151, v65
	v_exp_f32_e32 v152, v48
	v_exp_f32_e32 v153, v49
	v_exp_f32_e32 v167, v50
	v_exp_f32_e32 v169, v51
	v_exp_f32_e32 v201, v69
	v_exp_f32_e32 v208, v52
	v_mfma_f32_32x32x16_bf16 v[80:95], v[84:87], v[136:139], 0
	v_exp_f32_e32 v209, v55
	v_exp_f32_e32 v219, v74
	v_mfma_f32_32x32x16_bf16 v[96:111], v[154:157], v[132:135], v[96:111]
	v_exp_f32_e32 v155, v66
	v_exp_f32_e32 v156, v67
	v_exp_f32_e32 v157, v68
	v_mfma_f32_32x32x16_bf16 v[96:111], v[212:215], v[128:131], v[96:111]
	v_exp_f32_e32 v212, v72
	v_exp_f32_e32 v213, v73
	v_exp_f32_e32 v214, v56
	v_exp_f32_e32 v215, v57
	v_mfma_f32_32x32x16_bf16 v[96:111], v[224:227], v[124:127], v[96:111]
	v_exp_f32_e32 v224, v77
	v_exp_f32_e32 v225, v60
	v_exp_f32_e32 v226, v61
	v_exp_f32_e32 v227, v78
	v_mfma_f32_32x32x16_bf16 v[96:111], v[232:235], v[120:123], v[96:111]
	v_mfma_f32_32x32x16_bf16 v[96:111], v[240:243], v[116:119], v[96:111]
	v_mfma_f32_32x32x16_bf16 v[80:95], v[202:205], v[132:135], v[80:95]
	v_exp_f32_e32 v202, v53
	v_exp_f32_e32 v203, v70
	v_exp_f32_e32 v204, v71
	v_exp_f32_e32 v205, v54
	v_mfma_f32_32x32x16_bf16 v[80:95], v[220:223], v[128:131], v[80:95]
	v_exp_f32_e32 v220, v75
	v_exp_f32_e32 v221, v58
	v_exp_f32_e32 v222, v59
	v_exp_f32_e32 v223, v76
	v_mfma_f32_32x32x16_bf16 v[80:95], v[228:231], v[124:127], v[80:95]
	v_exp_f32_e32 v228, v79
	v_exp_f32_e32 v229, v62
	v_exp_f32_e32 v230, v63
	v_mfma_f32_32x32x16_bf16 v[80:95], v[236:239], v[120:123], v[80:95]
	ds_read_b128 v[48:51], v173 offset:49152
	ds_read_b128 v[52:55], v173 offset:53248
	ds_read_b128 v[56:59], v197 offset:49152
	ds_read_b128 v[60:63], v197 offset:53248
	ds_read_b128 v[64:67], v193 offset:49152
	ds_read_b128 v[68:71], v193 offset:53248
	ds_read_b128 v[72:75], v195 offset:49152
	ds_read_b128 v[76:79], v195 offset:53248
	v_pk_add_f32 v[32:33], v[32:33], v[150:151]
	v_cvt_pk_bf16_f32 v154, v150, v151
	v_add_f32_e32 v34, v34, v155
	v_add_f32_e32 v35, v35, v156
	v_cvt_pk_bf16_f32 v155, v155, v156
	v_add_f32_e32 v32, v32, v157
	v_add_f32_e32 v33, v33, v201
	v_cvt_pk_bf16_f32 v156, v157, v201
	v_add_f32_e32 v34, v34, v203
	v_add_f32_e32 v35, v35, v204
	v_cvt_pk_bf16_f32 v157, v203, v204
	v_mfma_f32_32x32x16_bf16 v[80:95], v[244:247], v[116:119], v[80:95]
	s_and_b64 vcc, exec, s[6:7]
	s_waitcnt lgkmcnt(0)
	v_mfma_f32_32x32x16_bf16 v[16:31], v[52:55], v[154:157], v[16:31]
	v_mfma_f32_32x32x16_bf16 v[0:15], v[48:51], v[154:157], v[0:15]
	v_pk_add_f32 v[32:33], v[32:33], v[212:213]
	v_cvt_pk_bf16_f32 v48, v212, v213
	v_add_f32_e32 v34, v34, v219
	v_add_f32_e32 v35, v35, v220
	v_cvt_pk_bf16_f32 v49, v219, v220
	v_add_f32_e32 v32, v32, v223
	v_add_f32_e32 v33, v33, v224
	v_cvt_pk_bf16_f32 v50, v223, v224
	v_cvt_pk_bf16_f32 v51, v227, v228
	v_add_f32_e32 v34, v34, v227
	v_add_f32_e32 v35, v35, v228
	v_mfma_f32_32x32x16_bf16 v[16:31], v[60:63], v[48:51], v[16:31]
	v_mfma_f32_32x32x16_bf16 v[0:15], v[56:59], v[48:51], v[0:15]
	v_pk_add_f32 v[32:33], v[32:33], v[152:153]
	v_cvt_pk_bf16_f32 v52, v152, v153
	v_add_f32_e32 v34, v34, v167
	v_add_f32_e32 v35, v35, v169
	v_cvt_pk_bf16_f32 v53, v167, v169
	v_add_f32_e32 v32, v32, v208
	v_add_f32_e32 v33, v33, v202
	v_cvt_pk_bf16_f32 v54, v208, v202
	v_cvt_pk_bf16_f32 v55, v205, v209
	v_add_f32_e32 v34, v34, v205
	v_add_f32_e32 v35, v35, v209
	v_mfma_f32_32x32x16_bf16 v[16:31], v[68:71], v[52:55], v[16:31]
	v_mfma_f32_32x32x16_bf16 v[0:15], v[64:67], v[52:55], v[0:15]
	v_pk_add_f32 v[32:33], v[32:33], v[214:215]
	v_cvt_pk_bf16_f32 v48, v214, v215
	v_add_f32_e32 v34, v34, v221
	v_add_f32_e32 v35, v35, v222
	v_cvt_pk_bf16_f32 v49, v221, v222
	v_add_f32_e32 v32, v32, v225
	v_add_f32_e32 v33, v33, v226
	v_cvt_pk_bf16_f32 v50, v225, v226
	v_cvt_pk_bf16_f32 v51, v229, v230
	v_add_f32_e32 v34, v34, v229
	v_add_f32_e32 v35, v35, v230
	v_mfma_f32_32x32x16_bf16 v[16:31], v[76:79], v[48:51], v[16:31]
	v_mfma_f32_32x32x16_bf16 v[0:15], v[72:75], v[48:51], v[0:15]
	s_cbranch_vccnz .LBB0_1196
	v_pk_add_f32 v[102:103], v[102:103], v[172:173] op_sel_hi:[1,0] neg_lo:[0,1] neg_hi:[0,1]
	v_pk_add_f32 v[110:111], v[110:111], v[172:173] op_sel_hi:[1,0] neg_lo:[0,1] neg_hi:[0,1]
	v_pk_add_f32 v[96:97], v[96:97], v[172:173] op_sel_hi:[1,0] neg_lo:[0,1] neg_hi:[0,1]
	v_pk_add_f32 v[98:99], v[98:99], v[172:173] op_sel_hi:[1,0] neg_lo:[0,1] neg_hi:[0,1]
	v_pk_add_f32 v[100:101], v[100:101], v[172:173] op_sel_hi:[1,0] neg_lo:[0,1] neg_hi:[0,1]
	v_pk_add_f32 v[104:105], v[104:105], v[172:173] op_sel_hi:[1,0] neg_lo:[0,1] neg_hi:[0,1]
	v_pk_add_f32 v[106:107], v[106:107], v[172:173] op_sel_hi:[1,0] neg_lo:[0,1] neg_hi:[0,1]
	v_pk_add_f32 v[108:109], v[108:109], v[172:173] op_sel_hi:[1,0] neg_lo:[0,1] neg_hi:[0,1]
	v_pk_add_f32 v[94:95], v[94:95], v[172:173] op_sel_hi:[1,0] neg_lo:[0,1] neg_hi:[0,1]
	v_max_f32_e32 v50, v102, v103
	v_max_f32_e32 v53, v110, v111
	v_pk_add_f32 v[82:83], v[82:83], v[172:173] op_sel_hi:[1,0] neg_lo:[0,1] neg_hi:[0,1]
	v_pk_add_f32 v[86:87], v[86:87], v[172:173] op_sel_hi:[1,0] neg_lo:[0,1] neg_hi:[0,1]
	v_pk_add_f32 v[88:89], v[88:89], v[172:173] op_sel_hi:[1,0] neg_lo:[0,1] neg_hi:[0,1]
	v_pk_add_f32 v[90:91], v[90:91], v[172:173] op_sel_hi:[1,0] neg_lo:[0,1] neg_hi:[0,1]
	v_pk_add_f32 v[92:93], v[92:93], v[172:173] op_sel_hi:[1,0] neg_lo:[0,1] neg_hi:[0,1]
	v_max_f32_e32 v48, v96, v97
	v_max_f32_e32 v49, v98, v99
	v_max3_f32 v50, v100, v101, v50
	v_max_f32_e32 v51, v104, v105
	v_max_f32_e32 v52, v106, v107
	v_max3_f32 v53, v108, v109, v53
	v_max_f32_e32 v54, v94, v95
	v_pk_add_f32 v[80:81], v[80:81], v[172:173] op_sel_hi:[1,0] neg_lo:[0,1] neg_hi:[0,1]
	v_pk_add_f32 v[84:85], v[84:85], v[172:173] op_sel_hi:[1,0] neg_lo:[0,1] neg_hi:[0,1]
	v_max3_f32 v48, v48, v49, v50
	v_max3_f32 v49, v51, v52, v53
	v_max_f32_e32 v50, v82, v83
	v_max_f32_e32 v51, v86, v87
	v_max_f32_e32 v52, v88, v89
	v_max_f32_e32 v53, v90, v91
	v_max3_f32 v54, v92, v93, v54
	v_max3_f32 v50, v80, v81, v50
	v_max3_f32 v51, v84, v85, v51
	v_max3_f32 v52, v52, v53, v54
	v_max3_f32 v50, v50, v51, v52
	v_max3_f32 v48, v48, v49, v50
	ds_bpermute_b32 v49, v218, v48
	s_mov_b32 s14, 0x41000000
	s_waitcnt lgkmcnt(0)
	v_max_f32_e32 v49, v49, v49
	v_max_f32_e32 v48, v48, v49
	v_cmp_lt_f32_e32 vcc, s14, v48
	s_cbranch_vccz .LBB0_1196
	v_max_f32_e32 v48, v48, v48
	v_max_f32_e32 v49, 0, v48
	v_exp_f32_e64 v48, -v49
	v_sub_f32_e32 v96, v96, v49
	v_sub_f32_e32 v97, v97, v49
	v_sub_f32_e32 v98, v98, v49
	v_sub_f32_e32 v99, v99, v49
	v_sub_f32_e32 v100, v100, v49
	v_sub_f32_e32 v101, v101, v49
	v_sub_f32_e32 v102, v102, v49
	v_sub_f32_e32 v103, v103, v49
	v_sub_f32_e32 v104, v104, v49
	v_sub_f32_e32 v105, v105, v49
	v_sub_f32_e32 v106, v106, v49
	v_sub_f32_e32 v107, v107, v49
	v_sub_f32_e32 v108, v108, v49
	v_sub_f32_e32 v109, v109, v49
	v_sub_f32_e32 v110, v110, v49
	v_sub_f32_e32 v111, v111, v49
	v_sub_f32_e32 v80, v80, v49
	v_sub_f32_e32 v81, v81, v49
	v_sub_f32_e32 v82, v82, v49
	v_sub_f32_e32 v83, v83, v49
	v_sub_f32_e32 v84, v84, v49
	v_sub_f32_e32 v85, v85, v49
	v_sub_f32_e32 v86, v86, v49
	v_sub_f32_e32 v87, v87, v49
	v_sub_f32_e32 v88, v88, v49
	v_sub_f32_e32 v89, v89, v49
	v_sub_f32_e32 v90, v90, v49
	v_sub_f32_e32 v91, v91, v49
	v_sub_f32_e32 v92, v92, v49
	v_sub_f32_e32 v93, v93, v49
	v_sub_f32_e32 v94, v94, v49
	v_sub_f32_e32 v95, v95, v49
	v_pk_mul_f32 v[14:15], v[14:15], v[48:49] op_sel_hi:[1,0]
	v_pk_mul_f32 v[12:13], v[12:13], v[48:49] op_sel_hi:[1,0]
	v_pk_mul_f32 v[10:11], v[10:11], v[48:49] op_sel_hi:[1,0]
	v_pk_mul_f32 v[8:9], v[8:9], v[48:49] op_sel_hi:[1,0]
	v_pk_mul_f32 v[6:7], v[6:7], v[48:49] op_sel_hi:[1,0]
	v_pk_mul_f32 v[4:5], v[4:5], v[48:49] op_sel_hi:[1,0]
	v_pk_mul_f32 v[2:3], v[2:3], v[48:49] op_sel_hi:[1,0]
	v_pk_mul_f32 v[0:1], v[0:1], v[48:49] op_sel_hi:[1,0]
	v_pk_mul_f32 v[30:31], v[30:31], v[48:49] op_sel_hi:[1,0]
	v_pk_mul_f32 v[28:29], v[28:29], v[48:49] op_sel_hi:[1,0]
	v_pk_mul_f32 v[26:27], v[26:27], v[48:49] op_sel_hi:[1,0]
	v_pk_mul_f32 v[24:25], v[24:25], v[48:49] op_sel_hi:[1,0]
	v_pk_mul_f32 v[22:23], v[22:23], v[48:49] op_sel_hi:[1,0]
	v_pk_mul_f32 v[20:21], v[20:21], v[48:49] op_sel_hi:[1,0]
	v_pk_mul_f32 v[18:19], v[18:19], v[48:49] op_sel_hi:[1,0]
	v_pk_mul_f32 v[16:17], v[16:17], v[48:49] op_sel_hi:[1,0]
	v_pk_mul_f32 v[46:47], v[46:47], v[48:49] op_sel_hi:[1,0]
	v_pk_mul_f32 v[44:45], v[44:45], v[48:49] op_sel_hi:[1,0]
	v_pk_mul_f32 v[42:43], v[42:43], v[48:49] op_sel_hi:[1,0]
	v_pk_mul_f32 v[40:41], v[40:41], v[48:49] op_sel_hi:[1,0]
	v_pk_mul_f32 v[38:39], v[38:39], v[48:49] op_sel_hi:[1,0]
	v_pk_mul_f32 v[36:37], v[36:37], v[48:49] op_sel_hi:[1,0]
	v_pk_mul_f32 v[34:35], v[34:35], v[48:49] op_sel_hi:[1,0]
	v_pk_mul_f32 v[32:33], v[32:33], v[48:49] op_sel_hi:[1,0]
	v_add_f32_e32 v172, v172, v49
.LBB0_1196:
	ds_read_b128 v[48:51], v199 offset:24576
	ds_read_b128 v[52:55], v199 offset:30720
	ds_read_b128 v[154:157], v200 offset:24576
	ds_read_b128 v[202:205], v200 offset:30720
	ds_read_b128 v[212:215], v199 offset:24640
	ds_read_b128 v[220:223], v199 offset:30784
	ds_read_b128 v[224:227], v200 offset:24640
	ds_read_b128 v[228:231], v200 offset:30784
	ds_read_b128 v[232:235], v199 offset:24704
	ds_read_b128 v[236:239], v199 offset:30848
	ds_read_b128 v[240:243], v200 offset:24704
	ds_read_b128 v[244:247], v200 offset:30848
	s_waitcnt lgkmcnt(0)
	v_mfma_f32_32x32x16_bf16 v[64:79], v[48:51], v[136:139], 0
	v_exp_f32_e32 v150, v96
	v_exp_f32_e32 v151, v97
	v_exp_f32_e32 v152, v80
	v_exp_f32_e32 v153, v81
	v_exp_f32_e32 v167, v82
	v_exp_f32_e32 v169, v83
	v_exp_f32_e32 v201, v101
	v_mfma_f32_32x32x16_bf16 v[48:63], v[52:55], v[136:139], 0
	v_exp_f32_e32 v208, v84
	v_exp_f32_e32 v209, v87
	v_exp_f32_e32 v219, v106
	v_mfma_f32_32x32x16_bf16 v[64:79], v[154:157], v[132:135], v[64:79]
	v_exp_f32_e32 v155, v98
	v_exp_f32_e32 v156, v99
	v_exp_f32_e32 v157, v100
	v_mfma_f32_32x32x16_bf16 v[64:79], v[212:215], v[128:131], v[64:79]
	v_exp_f32_e32 v212, v104
	v_exp_f32_e32 v213, v105
	v_exp_f32_e32 v214, v88
	v_exp_f32_e32 v215, v89
	v_mfma_f32_32x32x16_bf16 v[64:79], v[224:227], v[124:127], v[64:79]
	v_exp_f32_e32 v224, v109
	v_exp_f32_e32 v225, v92
	v_exp_f32_e32 v226, v93
	v_exp_f32_e32 v227, v110
	v_mfma_f32_32x32x16_bf16 v[64:79], v[232:235], v[120:123], v[64:79]
	v_mfma_f32_32x32x16_bf16 v[64:79], v[240:243], v[116:119], v[64:79]
	v_mfma_f32_32x32x16_bf16 v[48:63], v[202:205], v[132:135], v[48:63]
	v_exp_f32_e32 v202, v85
	v_exp_f32_e32 v203, v102
	v_exp_f32_e32 v204, v103
	v_exp_f32_e32 v205, v86
	v_mfma_f32_32x32x16_bf16 v[48:63], v[220:223], v[128:131], v[48:63]
	v_exp_f32_e32 v220, v107
	v_exp_f32_e32 v221, v90
	v_exp_f32_e32 v222, v91
	v_exp_f32_e32 v223, v108
	v_mfma_f32_32x32x16_bf16 v[48:63], v[228:231], v[124:127], v[48:63]
	v_exp_f32_e32 v228, v111
	v_exp_f32_e32 v229, v94
	v_exp_f32_e32 v230, v95
	v_mfma_f32_32x32x16_bf16 v[48:63], v[236:239], v[120:123], v[48:63]
	ds_read_b128 v[80:83], v173 offset:57344
	ds_read_b128 v[84:87], v173 offset:61440
	ds_read_b128 v[88:91], v197 offset:57344
	ds_read_b128 v[92:95], v197 offset:61440
	ds_read_b128 v[96:99], v193 offset:57344
	ds_read_b128 v[100:103], v193 offset:61440
	ds_read_b128 v[104:107], v195 offset:57344
	ds_read_b128 v[108:111], v195 offset:61440
	v_pk_add_f32 v[32:33], v[32:33], v[150:151]
	v_cvt_pk_bf16_f32 v154, v150, v151
	v_add_f32_e32 v34, v34, v155
	v_add_f32_e32 v35, v35, v156
	v_cvt_pk_bf16_f32 v155, v155, v156
	v_add_f32_e32 v32, v32, v157
	v_add_f32_e32 v33, v33, v201
	v_cvt_pk_bf16_f32 v156, v157, v201
	v_add_f32_e32 v34, v34, v203
	v_add_f32_e32 v35, v35, v204
	v_cvt_pk_bf16_f32 v157, v203, v204
	v_mfma_f32_32x32x16_bf16 v[48:63], v[244:247], v[116:119], v[48:63]
	s_cmp_eq_u32 s64, 0
	s_cbranch_scc1 .Lmla_late_skip0
	s_waitcnt vmcnt(0)
	s_barrier
.Lmla_late_skip0:
	s_and_b64 vcc, exec, s[6:7]
	s_waitcnt lgkmcnt(0)
	v_mfma_f32_32x32x16_bf16 v[16:31], v[84:87], v[154:157], v[16:31]
	v_mfma_f32_32x32x16_bf16 v[0:15], v[80:83], v[154:157], v[0:15]
	v_pk_add_f32 v[32:33], v[32:33], v[212:213]
	v_cvt_pk_bf16_f32 v80, v212, v213
	v_add_f32_e32 v34, v34, v219
	v_add_f32_e32 v35, v35, v220
	v_cvt_pk_bf16_f32 v81, v219, v220
	v_add_f32_e32 v32, v32, v223
	v_add_f32_e32 v33, v33, v224
	v_cvt_pk_bf16_f32 v82, v223, v224
	v_cvt_pk_bf16_f32 v83, v227, v228
	v_add_f32_e32 v34, v34, v227
	v_add_f32_e32 v35, v35, v228
	v_mfma_f32_32x32x16_bf16 v[16:31], v[92:95], v[80:83], v[16:31]
	v_mfma_f32_32x32x16_bf16 v[0:15], v[88:91], v[80:83], v[0:15]
	v_pk_add_f32 v[32:33], v[32:33], v[152:153]
	v_cvt_pk_bf16_f32 v84, v152, v153
	v_add_f32_e32 v34, v34, v167
	v_add_f32_e32 v35, v35, v169
	v_cvt_pk_bf16_f32 v85, v167, v169
	v_add_f32_e32 v32, v32, v208
	v_add_f32_e32 v33, v33, v202
	v_cvt_pk_bf16_f32 v86, v208, v202
	v_cvt_pk_bf16_f32 v87, v205, v209
	v_add_f32_e32 v34, v34, v205
	v_add_f32_e32 v35, v35, v209
	v_mfma_f32_32x32x16_bf16 v[16:31], v[100:103], v[84:87], v[16:31]
	v_mfma_f32_32x32x16_bf16 v[0:15], v[96:99], v[84:87], v[0:15]
	v_pk_add_f32 v[32:33], v[32:33], v[214:215]
	v_cvt_pk_bf16_f32 v80, v214, v215
	v_add_f32_e32 v34, v34, v221
	v_add_f32_e32 v35, v35, v222
	v_cvt_pk_bf16_f32 v81, v221, v222
	v_add_f32_e32 v32, v32, v225
	v_add_f32_e32 v33, v33, v226
	v_cvt_pk_bf16_f32 v82, v225, v226
	v_cvt_pk_bf16_f32 v83, v229, v230
	v_add_f32_e32 v34, v34, v229
	v_add_f32_e32 v35, v35, v230
	v_mfma_f32_32x32x16_bf16 v[16:31], v[108:111], v[80:83], v[16:31]
	v_mfma_f32_32x32x16_bf16 v[0:15], v[104:107], v[80:83], v[0:15]
	s_cbranch_vccnz .LBB0_1199
	v_pk_add_f32 v[70:71], v[70:71], v[172:173] op_sel_hi:[1,0] neg_lo:[0,1] neg_hi:[0,1]
	v_pk_add_f32 v[78:79], v[78:79], v[172:173] op_sel_hi:[1,0] neg_lo:[0,1] neg_hi:[0,1]
	v_pk_add_f32 v[64:65], v[64:65], v[172:173] op_sel_hi:[1,0] neg_lo:[0,1] neg_hi:[0,1]
	v_pk_add_f32 v[66:67], v[66:67], v[172:173] op_sel_hi:[1,0] neg_lo:[0,1] neg_hi:[0,1]
	v_pk_add_f32 v[68:69], v[68:69], v[172:173] op_sel_hi:[1,0] neg_lo:[0,1] neg_hi:[0,1]
	v_pk_add_f32 v[72:73], v[72:73], v[172:173] op_sel_hi:[1,0] neg_lo:[0,1] neg_hi:[0,1]
	v_pk_add_f32 v[74:75], v[74:75], v[172:173] op_sel_hi:[1,0] neg_lo:[0,1] neg_hi:[0,1]
	v_pk_add_f32 v[76:77], v[76:77], v[172:173] op_sel_hi:[1,0] neg_lo:[0,1] neg_hi:[0,1]
	v_pk_add_f32 v[62:63], v[62:63], v[172:173] op_sel_hi:[1,0] neg_lo:[0,1] neg_hi:[0,1]
	v_max_f32_e32 v82, v70, v71
	v_max_f32_e32 v85, v78, v79
	v_pk_add_f32 v[50:51], v[50:51], v[172:173] op_sel_hi:[1,0] neg_lo:[0,1] neg_hi:[0,1]
	v_pk_add_f32 v[54:55], v[54:55], v[172:173] op_sel_hi:[1,0] neg_lo:[0,1] neg_hi:[0,1]
	v_pk_add_f32 v[56:57], v[56:57], v[172:173] op_sel_hi:[1,0] neg_lo:[0,1] neg_hi:[0,1]
	v_pk_add_f32 v[58:59], v[58:59], v[172:173] op_sel_hi:[1,0] neg_lo:[0,1] neg_hi:[0,1]
	v_pk_add_f32 v[60:61], v[60:61], v[172:173] op_sel_hi:[1,0] neg_lo:[0,1] neg_hi:[0,1]
	v_max_f32_e32 v80, v64, v65
	v_max_f32_e32 v81, v66, v67
	v_max3_f32 v82, v68, v69, v82
	v_max_f32_e32 v83, v72, v73
	v_max_f32_e32 v84, v74, v75
	v_max3_f32 v85, v76, v77, v85
	v_max_f32_e32 v86, v62, v63
	v_pk_add_f32 v[48:49], v[48:49], v[172:173] op_sel_hi:[1,0] neg_lo:[0,1] neg_hi:[0,1]
	v_pk_add_f32 v[52:53], v[52:53], v[172:173] op_sel_hi:[1,0] neg_lo:[0,1] neg_hi:[0,1]
	v_max3_f32 v80, v80, v81, v82
	v_max3_f32 v81, v83, v84, v85
	v_max_f32_e32 v82, v50, v51
	v_max_f32_e32 v83, v54, v55
	v_max_f32_e32 v84, v56, v57
	v_max_f32_e32 v85, v58, v59
	v_max3_f32 v86, v60, v61, v86
	v_max3_f32 v82, v48, v49, v82
	v_max3_f32 v83, v52, v53, v83
	v_max3_f32 v84, v84, v85, v86
	v_max3_f32 v82, v82, v83, v84
	v_max3_f32 v80, v80, v81, v82
	ds_bpermute_b32 v81, v218, v80
	s_mov_b32 s14, 0x41000000
	s_waitcnt lgkmcnt(0)
	v_max_f32_e32 v81, v81, v81
	v_max_f32_e32 v80, v80, v81
	v_cmp_lt_f32_e32 vcc, s14, v80
	s_cbranch_vccz .LBB0_1199
	v_max_f32_e32 v80, v80, v80
	v_max_f32_e32 v81, 0, v80
	v_exp_f32_e64 v80, -v81
	v_sub_f32_e32 v64, v64, v81
	v_sub_f32_e32 v65, v65, v81
	v_sub_f32_e32 v66, v66, v81
	v_sub_f32_e32 v67, v67, v81
	v_sub_f32_e32 v68, v68, v81
	v_sub_f32_e32 v69, v69, v81
	v_sub_f32_e32 v70, v70, v81
	v_sub_f32_e32 v71, v71, v81
	v_sub_f32_e32 v72, v72, v81
	v_sub_f32_e32 v73, v73, v81
	v_sub_f32_e32 v74, v74, v81
	v_sub_f32_e32 v75, v75, v81
	v_sub_f32_e32 v76, v76, v81
	v_sub_f32_e32 v77, v77, v81
	v_sub_f32_e32 v78, v78, v81
	v_sub_f32_e32 v79, v79, v81
	v_sub_f32_e32 v48, v48, v81
	v_sub_f32_e32 v49, v49, v81
	v_sub_f32_e32 v50, v50, v81
	v_sub_f32_e32 v51, v51, v81
	v_sub_f32_e32 v52, v52, v81
	v_sub_f32_e32 v53, v53, v81
	v_sub_f32_e32 v54, v54, v81
	v_sub_f32_e32 v55, v55, v81
	v_sub_f32_e32 v56, v56, v81
	v_sub_f32_e32 v57, v57, v81
	v_sub_f32_e32 v58, v58, v81
	v_sub_f32_e32 v59, v59, v81
	v_sub_f32_e32 v60, v60, v81
	v_sub_f32_e32 v61, v61, v81
	v_sub_f32_e32 v62, v62, v81
	v_sub_f32_e32 v63, v63, v81
	v_pk_mul_f32 v[14:15], v[14:15], v[80:81] op_sel_hi:[1,0]
	v_pk_mul_f32 v[12:13], v[12:13], v[80:81] op_sel_hi:[1,0]
	v_pk_mul_f32 v[10:11], v[10:11], v[80:81] op_sel_hi:[1,0]
	v_pk_mul_f32 v[8:9], v[8:9], v[80:81] op_sel_hi:[1,0]
	v_pk_mul_f32 v[6:7], v[6:7], v[80:81] op_sel_hi:[1,0]
	v_pk_mul_f32 v[4:5], v[4:5], v[80:81] op_sel_hi:[1,0]
	v_pk_mul_f32 v[2:3], v[2:3], v[80:81] op_sel_hi:[1,0]
	v_pk_mul_f32 v[0:1], v[0:1], v[80:81] op_sel_hi:[1,0]
	v_pk_mul_f32 v[30:31], v[30:31], v[80:81] op_sel_hi:[1,0]
	v_pk_mul_f32 v[28:29], v[28:29], v[80:81] op_sel_hi:[1,0]
	v_pk_mul_f32 v[26:27], v[26:27], v[80:81] op_sel_hi:[1,0]
	v_pk_mul_f32 v[24:25], v[24:25], v[80:81] op_sel_hi:[1,0]
	v_pk_mul_f32 v[22:23], v[22:23], v[80:81] op_sel_hi:[1,0]
	v_pk_mul_f32 v[20:21], v[20:21], v[80:81] op_sel_hi:[1,0]
	v_pk_mul_f32 v[18:19], v[18:19], v[80:81] op_sel_hi:[1,0]
	v_pk_mul_f32 v[16:17], v[16:17], v[80:81] op_sel_hi:[1,0]
	v_pk_mul_f32 v[46:47], v[46:47], v[80:81] op_sel_hi:[1,0]
	v_pk_mul_f32 v[44:45], v[44:45], v[80:81] op_sel_hi:[1,0]
	v_pk_mul_f32 v[42:43], v[42:43], v[80:81] op_sel_hi:[1,0]
	v_pk_mul_f32 v[40:41], v[40:41], v[80:81] op_sel_hi:[1,0]
	v_pk_mul_f32 v[38:39], v[38:39], v[80:81] op_sel_hi:[1,0]
	v_pk_mul_f32 v[36:37], v[36:37], v[80:81] op_sel_hi:[1,0]
	v_pk_mul_f32 v[34:35], v[34:35], v[80:81] op_sel_hi:[1,0]
	v_pk_mul_f32 v[32:33], v[32:33], v[80:81] op_sel_hi:[1,0]
	v_add_f32_e32 v172, v172, v81

.LBB0_1203:
	s_mov_b32 m0, s14
	s_mov_b64 s[14:15], 0x3600280
	global_load_lds_dwordx4 v[82:83], off
	v_lshl_add_u64 v[80:81], v[188:189], 0, s[14:15]
	s_sub_i32 m0, s62, s66
	s_add_i32 m0, m0, 0x8000
	v_exp_f32_e32 v150, v64
	global_load_lds_dwordx4 v[80:81], off
	ds_read_b128 v[80:83], v199 offset:36864
	ds_read_b128 v[84:87], v199 offset:43008
	ds_read_b128 v[154:157], v200 offset:36864
	ds_read_b128 v[186:189], v200 offset:43008
	ds_read_b128 v[202:205], v199 offset:36928
	ds_read_b128 v[212:215], v199 offset:43072
	ds_read_b128 v[220:223], v200 offset:36928
	ds_read_b128 v[224:227], v200 offset:43072
	ds_read_b128 v[228:231], v199 offset:36992
	ds_read_b128 v[232:235], v199 offset:43136
	ds_read_b128 v[236:239], v200 offset:36992
	ds_read_b128 v[240:243], v200 offset:43136
	s_waitcnt lgkmcnt(0)
	v_mfma_f32_32x32x16_bf16 v[96:111], v[80:83], v[136:139], 0
	v_exp_f32_e32 v151, v65
	v_exp_f32_e32 v152, v48
	v_exp_f32_e32 v153, v49
	v_exp_f32_e32 v167, v50
	v_exp_f32_e32 v169, v51
	v_exp_f32_e32 v190, v69
	v_exp_f32_e32 v191, v52
	v_mfma_f32_32x32x16_bf16 v[80:95], v[84:87], v[136:139], 0
	v_exp_f32_e32 v201, v55
	v_exp_f32_e32 v208, v74
	v_exp_f32_e32 v209, v75
	v_exp_f32_e32 v219, v60
	v_mfma_f32_32x32x16_bf16 v[96:111], v[154:157], v[132:135], v[96:111]
	v_exp_f32_e32 v155, v66
	v_exp_f32_e32 v156, v67
	v_exp_f32_e32 v157, v68
	v_mfma_f32_32x32x16_bf16 v[96:111], v[202:205], v[128:131], v[96:111]
	v_exp_f32_e32 v202, v72
	v_exp_f32_e32 v203, v73
	v_exp_f32_e32 v204, v56
	v_exp_f32_e32 v205, v57
	v_mfma_f32_32x32x16_bf16 v[96:111], v[220:223], v[124:127], v[96:111]
	v_exp_f32_e32 v220, v61
	v_exp_f32_e32 v221, v78
	v_exp_f32_e32 v222, v79
	v_exp_f32_e32 v223, v62
	v_mfma_f32_32x32x16_bf16 v[96:111], v[228:231], v[120:123], v[96:111]
	v_mfma_f32_32x32x16_bf16 v[96:111], v[236:239], v[116:119], v[96:111]
	v_mfma_f32_32x32x16_bf16 v[80:95], v[186:189], v[132:135], v[80:95]
	v_exp_f32_e32 v186, v53
	v_exp_f32_e32 v187, v70
	v_exp_f32_e32 v188, v71
	v_exp_f32_e32 v189, v54
	v_mfma_f32_32x32x16_bf16 v[80:95], v[212:215], v[128:131], v[80:95]
	v_exp_f32_e32 v212, v58
	v_exp_f32_e32 v213, v59
	v_exp_f32_e32 v214, v76
	v_exp_f32_e32 v215, v77
	v_mfma_f32_32x32x16_bf16 v[80:95], v[224:227], v[124:127], v[80:95]
	v_exp_f32_e32 v224, v63
	v_mfma_f32_32x32x16_bf16 v[80:95], v[232:235], v[120:123], v[80:95]
	ds_read_b128 v[48:51], v192 offset:16384
	ds_read_b128 v[52:55], v192 offset:20480
	ds_read_b128 v[56:59], v198 offset:16384
	ds_read_b128 v[60:63], v198 offset:20480
	ds_read_b128 v[64:67], v194 offset:16384
	ds_read_b128 v[68:71], v194 offset:20480
	ds_read_b128 v[72:75], v196 offset:16384
	ds_read_b128 v[76:79], v196 offset:20480
	v_pk_add_f32 v[32:33], v[32:33], v[150:151]
	v_cvt_pk_bf16_f32 v154, v150, v151
	v_add_f32_e32 v34, v34, v155
	v_add_f32_e32 v35, v35, v156
	v_cvt_pk_bf16_f32 v155, v155, v156
	v_add_f32_e32 v32, v32, v157
	v_add_f32_e32 v33, v33, v190
	v_cvt_pk_bf16_f32 v156, v157, v190
	v_add_f32_e32 v34, v34, v187
	v_add_f32_e32 v35, v35, v188
	v_cvt_pk_bf16_f32 v157, v187, v188
	v_mfma_f32_32x32x16_bf16 v[80:95], v[240:243], v[116:119], v[80:95]
	s_and_b64 vcc, exec, s[6:7]
	s_waitcnt lgkmcnt(0)
	v_mfma_f32_32x32x16_bf16 v[16:31], v[52:55], v[154:157], v[16:31]
	v_mfma_f32_32x32x16_bf16 v[0:15], v[48:51], v[154:157], v[0:15]
	v_pk_add_f32 v[32:33], v[32:33], v[202:203]
	v_cvt_pk_bf16_f32 v48, v202, v203
	v_pk_add_f32 v[34:35], v[34:35], v[208:209]
	v_cvt_pk_bf16_f32 v49, v208, v209
	v_pk_add_f32 v[32:33], v[32:33], v[214:215]
	v_cvt_pk_bf16_f32 v50, v214, v215
	v_cvt_pk_bf16_f32 v51, v221, v222
	v_add_f32_e32 v34, v34, v221
	v_add_f32_e32 v35, v35, v222
	v_mfma_f32_32x32x16_bf16 v[16:31], v[60:63], v[48:51], v[16:31]
	v_mfma_f32_32x32x16_bf16 v[0:15], v[56:59], v[48:51], v[0:15]
	v_pk_add_f32 v[32:33], v[32:33], v[152:153]
	v_cvt_pk_bf16_f32 v52, v152, v153
	v_add_f32_e32 v34, v34, v167
	v_add_f32_e32 v35, v35, v169
	v_cvt_pk_bf16_f32 v53, v167, v169
	v_add_f32_e32 v32, v32, v191
	v_add_f32_e32 v33, v33, v186
	v_cvt_pk_bf16_f32 v54, v191, v186
	v_cvt_pk_bf16_f32 v55, v189, v201
	v_add_f32_e32 v34, v34, v189
	v_add_f32_e32 v35, v35, v201
	v_mfma_f32_32x32x16_bf16 v[16:31], v[68:71], v[52:55], v[16:31]
	v_mfma_f32_32x32x16_bf16 v[0:15], v[64:67], v[52:55], v[0:15]
	v_pk_add_f32 v[32:33], v[32:33], v[204:205]
	v_cvt_pk_bf16_f32 v48, v204, v205
	v_pk_add_f32 v[34:35], v[34:35], v[212:213]
	v_cvt_pk_bf16_f32 v49, v212, v213
	v_add_f32_e32 v32, v32, v219
	v_add_f32_e32 v33, v33, v220
	v_cvt_pk_bf16_f32 v50, v219, v220
	v_cvt_pk_bf16_f32 v51, v223, v224
	v_add_f32_e32 v34, v34, v223
	v_add_f32_e32 v35, v35, v224
	v_mfma_f32_32x32x16_bf16 v[16:31], v[76:79], v[48:51], v[16:31]
	v_mfma_f32_32x32x16_bf16 v[0:15], v[72:75], v[48:51], v[0:15]
	s_cbranch_vccnz .LBB0_1206
	v_pk_add_f32 v[102:103], v[102:103], v[172:173] op_sel_hi:[1,0] neg_lo:[0,1] neg_hi:[0,1]
	v_pk_add_f32 v[110:111], v[110:111], v[172:173] op_sel_hi:[1,0] neg_lo:[0,1] neg_hi:[0,1]
	v_pk_add_f32 v[96:97], v[96:97], v[172:173] op_sel_hi:[1,0] neg_lo:[0,1] neg_hi:[0,1]
	v_pk_add_f32 v[98:99], v[98:99], v[172:173] op_sel_hi:[1,0] neg_lo:[0,1] neg_hi:[0,1]
	v_pk_add_f32 v[100:101], v[100:101], v[172:173] op_sel_hi:[1,0] neg_lo:[0,1] neg_hi:[0,1]
	v_pk_add_f32 v[104:105], v[104:105], v[172:173] op_sel_hi:[1,0] neg_lo:[0,1] neg_hi:[0,1]
	v_pk_add_f32 v[106:107], v[106:107], v[172:173] op_sel_hi:[1,0] neg_lo:[0,1] neg_hi:[0,1]
	v_pk_add_f32 v[108:109], v[108:109], v[172:173] op_sel_hi:[1,0] neg_lo:[0,1] neg_hi:[0,1]
	v_pk_add_f32 v[94:95], v[94:95], v[172:173] op_sel_hi:[1,0] neg_lo:[0,1] neg_hi:[0,1]
	v_max_f32_e32 v50, v102, v103
	v_max_f32_e32 v53, v110, v111
	v_pk_add_f32 v[82:83], v[82:83], v[172:173] op_sel_hi:[1,0] neg_lo:[0,1] neg_hi:[0,1]
	v_pk_add_f32 v[86:87], v[86:87], v[172:173] op_sel_hi:[1,0] neg_lo:[0,1] neg_hi:[0,1]
	v_pk_add_f32 v[88:89], v[88:89], v[172:173] op_sel_hi:[1,0] neg_lo:[0,1] neg_hi:[0,1]
	v_pk_add_f32 v[90:91], v[90:91], v[172:173] op_sel_hi:[1,0] neg_lo:[0,1] neg_hi:[0,1]
	v_pk_add_f32 v[92:93], v[92:93], v[172:173] op_sel_hi:[1,0] neg_lo:[0,1] neg_hi:[0,1]
	v_max_f32_e32 v48, v96, v97
	v_max_f32_e32 v49, v98, v99
	v_max3_f32 v50, v100, v101, v50
	v_max_f32_e32 v51, v104, v105
	v_max_f32_e32 v52, v106, v107
	v_max3_f32 v53, v108, v109, v53
	v_max_f32_e32 v54, v94, v95
	v_pk_add_f32 v[80:81], v[80:81], v[172:173] op_sel_hi:[1,0] neg_lo:[0,1] neg_hi:[0,1]
	v_pk_add_f32 v[84:85], v[84:85], v[172:173] op_sel_hi:[1,0] neg_lo:[0,1] neg_hi:[0,1]
	v_max3_f32 v48, v48, v49, v50
	v_max3_f32 v49, v51, v52, v53
	v_max_f32_e32 v50, v82, v83
	v_max_f32_e32 v51, v86, v87
	v_max_f32_e32 v52, v88, v89
	v_max_f32_e32 v53, v90, v91
	v_max3_f32 v54, v92, v93, v54
	v_max3_f32 v50, v80, v81, v50
	v_max3_f32 v51, v84, v85, v51
	v_max3_f32 v52, v52, v53, v54
	v_max3_f32 v50, v50, v51, v52
	v_max3_f32 v48, v48, v49, v50
	ds_bpermute_b32 v49, v218, v48
	s_mov_b32 s14, 0x41000000
	s_waitcnt lgkmcnt(0)
	v_max_f32_e32 v49, v49, v49
	v_max_f32_e32 v48, v48, v49
	v_cmp_lt_f32_e32 vcc, s14, v48
	s_cbranch_vccz .LBB0_1206
	v_max_f32_e32 v48, v48, v48
	v_max_f32_e32 v49, 0, v48
	v_exp_f32_e64 v48, -v49
	v_sub_f32_e32 v96, v96, v49
	v_sub_f32_e32 v97, v97, v49
	v_sub_f32_e32 v98, v98, v49
	v_sub_f32_e32 v99, v99, v49
	v_sub_f32_e32 v100, v100, v49
	v_sub_f32_e32 v101, v101, v49
	v_sub_f32_e32 v102, v102, v49
	v_sub_f32_e32 v103, v103, v49
	v_sub_f32_e32 v104, v104, v49
	v_sub_f32_e32 v105, v105, v49
	v_sub_f32_e32 v106, v106, v49
	v_sub_f32_e32 v107, v107, v49
	v_sub_f32_e32 v108, v108, v49
	v_sub_f32_e32 v109, v109, v49
	v_sub_f32_e32 v110, v110, v49
	v_sub_f32_e32 v111, v111, v49
	v_sub_f32_e32 v80, v80, v49
	v_sub_f32_e32 v81, v81, v49
	v_sub_f32_e32 v82, v82, v49
	v_sub_f32_e32 v83, v83, v49
	v_sub_f32_e32 v84, v84, v49
	v_sub_f32_e32 v85, v85, v49
	v_sub_f32_e32 v86, v86, v49
	v_sub_f32_e32 v87, v87, v49
	v_sub_f32_e32 v88, v88, v49
	v_sub_f32_e32 v89, v89, v49
	v_sub_f32_e32 v90, v90, v49
	v_sub_f32_e32 v91, v91, v49
	v_sub_f32_e32 v92, v92, v49
	v_sub_f32_e32 v93, v93, v49
	v_sub_f32_e32 v94, v94, v49
	v_sub_f32_e32 v95, v95, v49
	v_pk_mul_f32 v[14:15], v[14:15], v[48:49] op_sel_hi:[1,0]
	v_pk_mul_f32 v[12:13], v[12:13], v[48:49] op_sel_hi:[1,0]
	v_pk_mul_f32 v[10:11], v[10:11], v[48:49] op_sel_hi:[1,0]
	v_pk_mul_f32 v[8:9], v[8:9], v[48:49] op_sel_hi:[1,0]
	v_pk_mul_f32 v[6:7], v[6:7], v[48:49] op_sel_hi:[1,0]
	v_pk_mul_f32 v[4:5], v[4:5], v[48:49] op_sel_hi:[1,0]
	v_pk_mul_f32 v[2:3], v[2:3], v[48:49] op_sel_hi:[1,0]
	v_pk_mul_f32 v[0:1], v[0:1], v[48:49] op_sel_hi:[1,0]
	v_pk_mul_f32 v[30:31], v[30:31], v[48:49] op_sel_hi:[1,0]
	v_pk_mul_f32 v[28:29], v[28:29], v[48:49] op_sel_hi:[1,0]
	v_pk_mul_f32 v[26:27], v[26:27], v[48:49] op_sel_hi:[1,0]
	v_pk_mul_f32 v[24:25], v[24:25], v[48:49] op_sel_hi:[1,0]
	v_pk_mul_f32 v[22:23], v[22:23], v[48:49] op_sel_hi:[1,0]
	v_pk_mul_f32 v[20:21], v[20:21], v[48:49] op_sel_hi:[1,0]
	v_pk_mul_f32 v[18:19], v[18:19], v[48:49] op_sel_hi:[1,0]
	v_pk_mul_f32 v[16:17], v[16:17], v[48:49] op_sel_hi:[1,0]
	v_pk_mul_f32 v[46:47], v[46:47], v[48:49] op_sel_hi:[1,0]
	v_pk_mul_f32 v[44:45], v[44:45], v[48:49] op_sel_hi:[1,0]
	v_pk_mul_f32 v[42:43], v[42:43], v[48:49] op_sel_hi:[1,0]
	v_pk_mul_f32 v[40:41], v[40:41], v[48:49] op_sel_hi:[1,0]
	v_pk_mul_f32 v[38:39], v[38:39], v[48:49] op_sel_hi:[1,0]
	v_pk_mul_f32 v[36:37], v[36:37], v[48:49] op_sel_hi:[1,0]
	v_pk_mul_f32 v[34:35], v[34:35], v[48:49] op_sel_hi:[1,0]
	v_pk_mul_f32 v[32:33], v[32:33], v[48:49] op_sel_hi:[1,0]
	v_add_f32_e32 v172, v172, v49
.LBB0_1206:
	ds_read_b128 v[48:51], v199
	ds_read_b128 v[52:55], v199 offset:6144
	ds_read_b128 v[154:157], v200
	ds_read_b128 v[186:189], v200 offset:6144
	ds_read_b128 v[202:205], v199 offset:64
	ds_read_b128 v[212:215], v199 offset:6208
	ds_read_b128 v[220:223], v200 offset:64
	ds_read_b128 v[224:227], v200 offset:6208
	ds_read_b128 v[228:231], v199 offset:128
	ds_read_b128 v[232:235], v199 offset:6272
	ds_read_b128 v[236:239], v200 offset:128
	ds_read_b128 v[240:243], v200 offset:6272
	s_waitcnt lgkmcnt(0)
	v_mfma_f32_32x32x16_bf16 v[64:79], v[48:51], v[136:139], 0
	v_exp_f32_e32 v150, v96
	v_exp_f32_e32 v151, v97
	v_exp_f32_e32 v152, v80
	v_exp_f32_e32 v153, v81
	v_exp_f32_e32 v167, v82
	v_exp_f32_e32 v169, v83
	v_exp_f32_e32 v190, v101
	v_mfma_f32_32x32x16_bf16 v[48:63], v[52:55], v[136:139], 0
	v_exp_f32_e32 v191, v84
	v_exp_f32_e32 v201, v87
	v_exp_f32_e32 v208, v106
	v_exp_f32_e32 v209, v107
	v_exp_f32_e32 v219, v92
	v_mfma_f32_32x32x16_bf16 v[64:79], v[154:157], v[132:135], v[64:79]
	v_exp_f32_e32 v155, v98
	v_exp_f32_e32 v156, v99
	v_exp_f32_e32 v157, v100
	v_mfma_f32_32x32x16_bf16 v[64:79], v[202:205], v[128:131], v[64:79]
	v_exp_f32_e32 v202, v104
	v_exp_f32_e32 v203, v105
	v_exp_f32_e32 v204, v88
	v_exp_f32_e32 v205, v89
	v_mfma_f32_32x32x16_bf16 v[64:79], v[220:223], v[124:127], v[64:79]
	v_exp_f32_e32 v220, v93
	v_exp_f32_e32 v221, v110
	v_exp_f32_e32 v222, v111
	v_exp_f32_e32 v223, v94
	v_mfma_f32_32x32x16_bf16 v[64:79], v[228:231], v[120:123], v[64:79]
	v_mfma_f32_32x32x16_bf16 v[64:79], v[236:239], v[116:119], v[64:79]
	v_mfma_f32_32x32x16_bf16 v[48:63], v[186:189], v[132:135], v[48:63]
	v_exp_f32_e32 v186, v85
	v_exp_f32_e32 v187, v102
	v_exp_f32_e32 v188, v103
	v_exp_f32_e32 v189, v86
	v_mfma_f32_32x32x16_bf16 v[48:63], v[212:215], v[128:131], v[48:63]
	v_exp_f32_e32 v212, v90
	v_exp_f32_e32 v213, v91
	v_exp_f32_e32 v214, v108
	v_exp_f32_e32 v215, v109
	v_mfma_f32_32x32x16_bf16 v[48:63], v[224:227], v[124:127], v[48:63]
	v_exp_f32_e32 v224, v95
	v_mfma_f32_32x32x16_bf16 v[48:63], v[232:235], v[120:123], v[48:63]
	ds_read_b128 v[80:83], v192 offset:24576
	ds_read_b128 v[84:87], v192 offset:28672
	ds_read_b128 v[88:91], v198 offset:24576
	ds_read_b128 v[92:95], v198 offset:28672
	ds_read_b128 v[96:99], v194 offset:24576
	ds_read_b128 v[100:103], v194 offset:28672
	ds_read_b128 v[104:107], v196 offset:24576
	ds_read_b128 v[108:111], v196 offset:28672
	v_pk_add_f32 v[32:33], v[32:33], v[150:151]
	v_cvt_pk_bf16_f32 v154, v150, v151
	v_add_f32_e32 v34, v34, v155
	v_add_f32_e32 v35, v35, v156
	v_cvt_pk_bf16_f32 v155, v155, v156
	v_add_f32_e32 v32, v32, v157
	v_add_f32_e32 v33, v33, v190
	v_cvt_pk_bf16_f32 v156, v157, v190
	v_add_f32_e32 v34, v34, v187
	v_add_f32_e32 v35, v35, v188
	v_cvt_pk_bf16_f32 v157, v187, v188
	v_mfma_f32_32x32x16_bf16 v[48:63], v[240:243], v[116:119], v[48:63]
	s_cmp_eq_u32 s64, 0
	s_cbranch_scc1 .Lmla_late_skip1
	s_waitcnt vmcnt(0)
	s_barrier
.Lmla_late_skip1:
	s_and_b64 vcc, exec, s[6:7]
	s_waitcnt lgkmcnt(0)
	v_mfma_f32_32x32x16_bf16 v[16:31], v[84:87], v[154:157], v[16:31]
	v_mfma_f32_32x32x16_bf16 v[0:15], v[80:83], v[154:157], v[0:15]
	v_pk_add_f32 v[32:33], v[32:33], v[202:203]
	v_cvt_pk_bf16_f32 v80, v202, v203
	v_pk_add_f32 v[34:35], v[34:35], v[208:209]
	v_cvt_pk_bf16_f32 v81, v208, v209
	v_pk_add_f32 v[32:33], v[32:33], v[214:215]
	v_cvt_pk_bf16_f32 v82, v214, v215
	v_cvt_pk_bf16_f32 v83, v221, v222
	v_add_f32_e32 v34, v34, v221
	v_add_f32_e32 v35, v35, v222
	v_mfma_f32_32x32x16_bf16 v[16:31], v[92:95], v[80:83], v[16:31]
	v_mfma_f32_32x32x16_bf16 v[0:15], v[88:91], v[80:83], v[0:15]
	v_pk_add_f32 v[32:33], v[32:33], v[152:153]
	v_cvt_pk_bf16_f32 v84, v152, v153
	v_add_f32_e32 v34, v34, v167
	v_add_f32_e32 v35, v35, v169
	v_cvt_pk_bf16_f32 v85, v167, v169
	v_add_f32_e32 v32, v32, v191
	v_add_f32_e32 v33, v33, v186
	v_cvt_pk_bf16_f32 v86, v191, v186
	v_cvt_pk_bf16_f32 v87, v189, v201
	v_add_f32_e32 v34, v34, v189
	v_add_f32_e32 v35, v35, v201
	v_mfma_f32_32x32x16_bf16 v[16:31], v[100:103], v[84:87], v[16:31]
	v_mfma_f32_32x32x16_bf16 v[0:15], v[96:99], v[84:87], v[0:15]
	v_pk_add_f32 v[32:33], v[32:33], v[204:205]
	v_cvt_pk_bf16_f32 v80, v204, v205
	v_pk_add_f32 v[34:35], v[34:35], v[212:213]
	v_cvt_pk_bf16_f32 v81, v212, v213
	v_add_f32_e32 v32, v32, v219
	v_add_f32_e32 v33, v33, v220
	v_cvt_pk_bf16_f32 v82, v219, v220
	v_cvt_pk_bf16_f32 v83, v223, v224
	v_add_f32_e32 v34, v34, v223
	v_add_f32_e32 v35, v35, v224
	v_mfma_f32_32x32x16_bf16 v[16:31], v[108:111], v[80:83], v[16:31]
	v_mfma_f32_32x32x16_bf16 v[0:15], v[104:107], v[80:83], v[0:15]
	s_cbranch_vccnz .LBB0_1188
	v_pk_add_f32 v[70:71], v[70:71], v[172:173] op_sel_hi:[1,0] neg_lo:[0,1] neg_hi:[0,1]
	v_pk_add_f32 v[78:79], v[78:79], v[172:173] op_sel_hi:[1,0] neg_lo:[0,1] neg_hi:[0,1]
	v_pk_add_f32 v[64:65], v[64:65], v[172:173] op_sel_hi:[1,0] neg_lo:[0,1] neg_hi:[0,1]
	v_pk_add_f32 v[66:67], v[66:67], v[172:173] op_sel_hi:[1,0] neg_lo:[0,1] neg_hi:[0,1]
	v_pk_add_f32 v[68:69], v[68:69], v[172:173] op_sel_hi:[1,0] neg_lo:[0,1] neg_hi:[0,1]
	v_pk_add_f32 v[72:73], v[72:73], v[172:173] op_sel_hi:[1,0] neg_lo:[0,1] neg_hi:[0,1]
	v_pk_add_f32 v[74:75], v[74:75], v[172:173] op_sel_hi:[1,0] neg_lo:[0,1] neg_hi:[0,1]
	v_pk_add_f32 v[76:77], v[76:77], v[172:173] op_sel_hi:[1,0] neg_lo:[0,1] neg_hi:[0,1]
	v_pk_add_f32 v[62:63], v[62:63], v[172:173] op_sel_hi:[1,0] neg_lo:[0,1] neg_hi:[0,1]
	v_max_f32_e32 v82, v70, v71
	v_max_f32_e32 v85, v78, v79
	v_pk_add_f32 v[50:51], v[50:51], v[172:173] op_sel_hi:[1,0] neg_lo:[0,1] neg_hi:[0,1]
	v_pk_add_f32 v[54:55], v[54:55], v[172:173] op_sel_hi:[1,0] neg_lo:[0,1] neg_hi:[0,1]
	v_pk_add_f32 v[56:57], v[56:57], v[172:173] op_sel_hi:[1,0] neg_lo:[0,1] neg_hi:[0,1]
	v_pk_add_f32 v[58:59], v[58:59], v[172:173] op_sel_hi:[1,0] neg_lo:[0,1] neg_hi:[0,1]
	v_pk_add_f32 v[60:61], v[60:61], v[172:173] op_sel_hi:[1,0] neg_lo:[0,1] neg_hi:[0,1]
	v_max_f32_e32 v80, v64, v65
	v_max_f32_e32 v81, v66, v67
	v_max3_f32 v82, v68, v69, v82
	v_max_f32_e32 v83, v72, v73
	v_max_f32_e32 v84, v74, v75
	v_max3_f32 v85, v76, v77, v85
	v_max_f32_e32 v86, v62, v63
	v_pk_add_f32 v[48:49], v[48:49], v[172:173] op_sel_hi:[1,0] neg_lo:[0,1] neg_hi:[0,1]
	v_pk_add_f32 v[52:53], v[52:53], v[172:173] op_sel_hi:[1,0] neg_lo:[0,1] neg_hi:[0,1]
	v_max3_f32 v80, v80, v81, v82
	v_max3_f32 v81, v83, v84, v85
	v_max_f32_e32 v82, v50, v51
	v_max_f32_e32 v83, v54, v55
	v_max_f32_e32 v84, v56, v57
	v_max_f32_e32 v85, v58, v59
	v_max3_f32 v86, v60, v61, v86
	v_max3_f32 v82, v48, v49, v82
	v_max3_f32 v83, v52, v53, v83
	v_max3_f32 v84, v84, v85, v86
	v_max3_f32 v82, v82, v83, v84
	v_max3_f32 v80, v80, v81, v82
	ds_bpermute_b32 v81, v218, v80
	s_mov_b32 s14, 0x41000000
	s_waitcnt lgkmcnt(0)
	v_max_f32_e32 v81, v81, v81
	v_max_f32_e32 v80, v80, v81
	v_cmp_lt_f32_e32 vcc, s14, v80
	s_cbranch_vccz .LBB0_1188
	v_max_f32_e32 v80, v80, v80
	v_max_f32_e32 v81, 0, v80
	v_exp_f32_e64 v80, -v81
	v_sub_f32_e32 v79, v79, v81
	v_sub_f32_e32 v78, v78, v81
	v_sub_f32_e32 v77, v77, v81
	v_sub_f32_e32 v76, v76, v81
	v_sub_f32_e32 v75, v75, v81
	v_sub_f32_e32 v74, v74, v81
	v_sub_f32_e32 v73, v73, v81
	v_sub_f32_e32 v72, v72, v81
	v_sub_f32_e32 v71, v71, v81
	v_sub_f32_e32 v70, v70, v81
	v_sub_f32_e32 v69, v69, v81
	v_sub_f32_e32 v68, v68, v81
	v_sub_f32_e32 v67, v67, v81
	v_sub_f32_e32 v66, v66, v81
	v_sub_f32_e32 v65, v65, v81
	v_sub_f32_e32 v64, v64, v81
	v_sub_f32_e32 v63, v63, v81
	v_sub_f32_e32 v62, v62, v81
	v_sub_f32_e32 v61, v61, v81
	v_sub_f32_e32 v60, v60, v81
	v_sub_f32_e32 v59, v59, v81
	v_sub_f32_e32 v58, v58, v81
	v_sub_f32_e32 v57, v57, v81
	v_sub_f32_e32 v56, v56, v81
	v_sub_f32_e32 v55, v55, v81
	v_sub_f32_e32 v54, v54, v81
	v_sub_f32_e32 v53, v53, v81
	v_sub_f32_e32 v52, v52, v81
	v_sub_f32_e32 v51, v51, v81
	v_sub_f32_e32 v50, v50, v81
	v_sub_f32_e32 v49, v49, v81
	v_sub_f32_e32 v48, v48, v81
	v_pk_mul_f32 v[14:15], v[14:15], v[80:81] op_sel_hi:[1,0]
	v_pk_mul_f32 v[12:13], v[12:13], v[80:81] op_sel_hi:[1,0]
	v_pk_mul_f32 v[10:11], v[10:11], v[80:81] op_sel_hi:[1,0]
	v_pk_mul_f32 v[8:9], v[8:9], v[80:81] op_sel_hi:[1,0]
	v_pk_mul_f32 v[6:7], v[6:7], v[80:81] op_sel_hi:[1,0]
	v_pk_mul_f32 v[4:5], v[4:5], v[80:81] op_sel_hi:[1,0]
	v_pk_mul_f32 v[2:3], v[2:3], v[80:81] op_sel_hi:[1,0]
	v_pk_mul_f32 v[0:1], v[0:1], v[80:81] op_sel_hi:[1,0]
	v_pk_mul_f32 v[30:31], v[30:31], v[80:81] op_sel_hi:[1,0]
	v_pk_mul_f32 v[28:29], v[28:29], v[80:81] op_sel_hi:[1,0]
	v_pk_mul_f32 v[26:27], v[26:27], v[80:81] op_sel_hi:[1,0]
	v_pk_mul_f32 v[24:25], v[24:25], v[80:81] op_sel_hi:[1,0]
	v_pk_mul_f32 v[22:23], v[22:23], v[80:81] op_sel_hi:[1,0]
	v_pk_mul_f32 v[20:21], v[20:21], v[80:81] op_sel_hi:[1,0]
	v_pk_mul_f32 v[18:19], v[18:19], v[80:81] op_sel_hi:[1,0]
	v_pk_mul_f32 v[16:17], v[16:17], v[80:81] op_sel_hi:[1,0]
	v_pk_mul_f32 v[46:47], v[46:47], v[80:81] op_sel_hi:[1,0]
	v_pk_mul_f32 v[44:45], v[44:45], v[80:81] op_sel_hi:[1,0]
	v_pk_mul_f32 v[42:43], v[42:43], v[80:81] op_sel_hi:[1,0]
	v_pk_mul_f32 v[40:41], v[40:41], v[80:81] op_sel_hi:[1,0]
	v_pk_mul_f32 v[38:39], v[38:39], v[80:81] op_sel_hi:[1,0]
	v_pk_mul_f32 v[36:37], v[36:37], v[80:81] op_sel_hi:[1,0]
	v_pk_mul_f32 v[34:35], v[34:35], v[80:81] op_sel_hi:[1,0]
	v_pk_mul_f32 v[32:33], v[32:33], v[80:81] op_sel_hi:[1,0]
	v_add_f32_e32 v172, v172, v81
	s_branch .LBB0_1188

.LBB0_1213:
	s_mov_b32 m0, s12
	v_lshl_add_u64 v[80:81], v[84:85], 0, s[8:9]
	s_mov_b64 s[8:9], 0x1f80
	global_load_lds_dwordx4 v[80:81], off
	v_lshl_add_u64 v[80:81], v[178:179], 0, s[8:9]
	s_add_i32 m0, s17, s66
	v_exp_f32_e32 v150, v64
	global_load_lds_dwordx4 v[80:81], off
	ds_read_b128 v[80:83], v199 offset:12288
	ds_read_b128 v[84:87], v199 offset:18432
	ds_read_b128 v[154:157], v200 offset:12288
	ds_read_b128 v[176:179], v200 offset:18432
	ds_read_b128 v[180:183], v199 offset:12352
	ds_read_b128 v[184:187], v199 offset:18496
	ds_read_b128 v[188:191], v200 offset:12352
	ds_read_b128 v[202:205], v200 offset:18496
	ds_read_b128 v[212:215], v199 offset:12416
	ds_read_b128 v[220:223], v199 offset:18560
	ds_read_b128 v[224:227], v200 offset:12416
	ds_read_b128 v[228:231], v200 offset:18560
	s_waitcnt lgkmcnt(0)
	v_mfma_f32_32x32x16_bf16 v[96:111], v[80:83], v[136:139], 0
	v_exp_f32_e32 v151, v65
	v_exp_f32_e32 v152, v48
	v_exp_f32_e32 v153, v49
	v_exp_f32_e32 v167, v50
	v_exp_f32_e32 v169, v51
	v_exp_f32_e32 v201, v77
	v_exp_f32_e32 v208, v62
	v_mfma_f32_32x32x16_bf16 v[80:95], v[84:87], v[136:139], 0
	v_exp_f32_e32 v209, v63
	v_mfma_f32_32x32x16_bf16 v[96:111], v[154:157], v[132:135], v[96:111]
	v_exp_f32_e32 v155, v66
	v_exp_f32_e32 v156, v67
	v_exp_f32_e32 v157, v68
	v_mfma_f32_32x32x16_bf16 v[96:111], v[180:183], v[128:131], v[96:111]
	v_exp_f32_e32 v180, v69
	v_exp_f32_e32 v181, v52
	v_exp_f32_e32 v182, v55
	v_exp_f32_e32 v183, v72
	v_mfma_f32_32x32x16_bf16 v[96:111], v[188:191], v[124:127], v[96:111]
	v_exp_f32_e32 v188, v73
	v_exp_f32_e32 v189, v58
	v_exp_f32_e32 v190, v59
	v_exp_f32_e32 v191, v76
	v_mfma_f32_32x32x16_bf16 v[96:111], v[212:215], v[120:123], v[96:111]
	v_mfma_f32_32x32x16_bf16 v[96:111], v[224:227], v[116:119], v[96:111]
	v_mfma_f32_32x32x16_bf16 v[80:95], v[176:179], v[132:135], v[80:95]
	v_exp_f32_e32 v176, v53
	v_exp_f32_e32 v177, v70
	v_exp_f32_e32 v178, v71
	v_exp_f32_e32 v179, v54
	v_mfma_f32_32x32x16_bf16 v[80:95], v[184:187], v[128:131], v[80:95]
	v_exp_f32_e32 v184, v56
	v_exp_f32_e32 v185, v57
	v_exp_f32_e32 v186, v74
	v_exp_f32_e32 v187, v75
	v_mfma_f32_32x32x16_bf16 v[80:95], v[202:205], v[124:127], v[80:95]
	v_exp_f32_e32 v202, v60
	v_exp_f32_e32 v203, v61
	v_exp_f32_e32 v204, v78
	v_exp_f32_e32 v205, v79
	v_mfma_f32_32x32x16_bf16 v[80:95], v[220:223], v[120:123], v[80:95]
	ds_read_b128 v[48:51], v173 offset:49152
	ds_read_b128 v[52:55], v173 offset:53248
	ds_read_b128 v[56:59], v197 offset:49152
	ds_read_b128 v[60:63], v197 offset:53248
	ds_read_b128 v[64:67], v193 offset:49152
	ds_read_b128 v[68:71], v193 offset:53248
	ds_read_b128 v[72:75], v195 offset:49152
	ds_read_b128 v[76:79], v195 offset:53248
	v_pk_add_f32 v[32:33], v[32:33], v[150:151]
	v_cvt_pk_bf16_f32 v154, v150, v151
	v_add_f32_e32 v34, v34, v155
	v_add_f32_e32 v35, v35, v156
	v_cvt_pk_bf16_f32 v155, v155, v156
	v_add_f32_e32 v32, v32, v157
	v_add_f32_e32 v33, v33, v180
	v_cvt_pk_bf16_f32 v156, v157, v180
	v_add_f32_e32 v34, v34, v177
	v_add_f32_e32 v35, v35, v178
	v_cvt_pk_bf16_f32 v157, v177, v178
	v_mfma_f32_32x32x16_bf16 v[80:95], v[228:231], v[116:119], v[80:95]
	s_and_b64 vcc, exec, s[6:7]
	s_waitcnt lgkmcnt(0)
	v_mfma_f32_32x32x16_bf16 v[16:31], v[52:55], v[154:157], v[16:31]
	v_mfma_f32_32x32x16_bf16 v[0:15], v[48:51], v[154:157], v[0:15]
	v_add_f32_e32 v32, v32, v183
	v_add_f32_e32 v33, v33, v188
	v_cvt_pk_bf16_f32 v48, v183, v188
	v_pk_add_f32 v[34:35], v[34:35], v[186:187]
	v_cvt_pk_bf16_f32 v49, v186, v187
	v_add_f32_e32 v32, v32, v191
	v_add_f32_e32 v33, v33, v201
	v_cvt_pk_bf16_f32 v50, v191, v201
	v_cvt_pk_bf16_f32 v51, v204, v205
	v_pk_add_f32 v[34:35], v[34:35], v[204:205]
	s_nop 0
	v_mfma_f32_32x32x16_bf16 v[16:31], v[60:63], v[48:51], v[16:31]
	v_mfma_f32_32x32x16_bf16 v[0:15], v[56:59], v[48:51], v[0:15]
	v_pk_add_f32 v[32:33], v[32:33], v[152:153]
	v_cvt_pk_bf16_f32 v52, v152, v153
	v_add_f32_e32 v34, v34, v167
	v_add_f32_e32 v35, v35, v169
	v_cvt_pk_bf16_f32 v53, v167, v169
	v_add_f32_e32 v32, v32, v181
	v_add_f32_e32 v33, v33, v176
	v_cvt_pk_bf16_f32 v54, v181, v176
	v_cvt_pk_bf16_f32 v55, v179, v182
	v_add_f32_e32 v34, v34, v179
	v_add_f32_e32 v35, v35, v182
	v_mfma_f32_32x32x16_bf16 v[16:31], v[68:71], v[52:55], v[16:31]
	v_mfma_f32_32x32x16_bf16 v[0:15], v[64:67], v[52:55], v[0:15]
	v_pk_add_f32 v[32:33], v[32:33], v[184:185]
	v_cvt_pk_bf16_f32 v48, v184, v185
	v_add_f32_e32 v34, v34, v189
	v_add_f32_e32 v35, v35, v190
	v_cvt_pk_bf16_f32 v49, v189, v190
	v_pk_add_f32 v[32:33], v[32:33], v[202:203]
	v_cvt_pk_bf16_f32 v50, v202, v203
	v_cvt_pk_bf16_f32 v51, v208, v209
	v_pk_add_f32 v[34:35], v[34:35], v[208:209]
	s_nop 0
	v_mfma_f32_32x32x16_bf16 v[16:31], v[76:79], v[48:51], v[16:31]
	v_mfma_f32_32x32x16_bf16 v[0:15], v[72:75], v[48:51], v[0:15]
	s_cbranch_vccnz .LBB0_1216
	v_pk_add_f32 v[102:103], v[102:103], v[172:173] op_sel_hi:[1,0] neg_lo:[0,1] neg_hi:[0,1]
	v_pk_add_f32 v[110:111], v[110:111], v[172:173] op_sel_hi:[1,0] neg_lo:[0,1] neg_hi:[0,1]
	v_pk_add_f32 v[96:97], v[96:97], v[172:173] op_sel_hi:[1,0] neg_lo:[0,1] neg_hi:[0,1]
	v_pk_add_f32 v[98:99], v[98:99], v[172:173] op_sel_hi:[1,0] neg_lo:[0,1] neg_hi:[0,1]
	v_pk_add_f32 v[100:101], v[100:101], v[172:173] op_sel_hi:[1,0] neg_lo:[0,1] neg_hi:[0,1]
	v_pk_add_f32 v[104:105], v[104:105], v[172:173] op_sel_hi:[1,0] neg_lo:[0,1] neg_hi:[0,1]
	v_pk_add_f32 v[106:107], v[106:107], v[172:173] op_sel_hi:[1,0] neg_lo:[0,1] neg_hi:[0,1]
	v_pk_add_f32 v[108:109], v[108:109], v[172:173] op_sel_hi:[1,0] neg_lo:[0,1] neg_hi:[0,1]
	v_pk_add_f32 v[94:95], v[94:95], v[172:173] op_sel_hi:[1,0] neg_lo:[0,1] neg_hi:[0,1]
	v_max_f32_e32 v50, v102, v103
	v_max_f32_e32 v53, v110, v111
	v_pk_add_f32 v[82:83], v[82:83], v[172:173] op_sel_hi:[1,0] neg_lo:[0,1] neg_hi:[0,1]
	v_pk_add_f32 v[86:87], v[86:87], v[172:173] op_sel_hi:[1,0] neg_lo:[0,1] neg_hi:[0,1]
	v_pk_add_f32 v[88:89], v[88:89], v[172:173] op_sel_hi:[1,0] neg_lo:[0,1] neg_hi:[0,1]
	v_pk_add_f32 v[90:91], v[90:91], v[172:173] op_sel_hi:[1,0] neg_lo:[0,1] neg_hi:[0,1]
	v_pk_add_f32 v[92:93], v[92:93], v[172:173] op_sel_hi:[1,0] neg_lo:[0,1] neg_hi:[0,1]
	v_max_f32_e32 v48, v96, v97
	v_max_f32_e32 v49, v98, v99
	v_max3_f32 v50, v100, v101, v50
	v_max_f32_e32 v51, v104, v105
	v_max_f32_e32 v52, v106, v107
	v_max3_f32 v53, v108, v109, v53
	v_max_f32_e32 v54, v94, v95
	v_pk_add_f32 v[80:81], v[80:81], v[172:173] op_sel_hi:[1,0] neg_lo:[0,1] neg_hi:[0,1]
	v_pk_add_f32 v[84:85], v[84:85], v[172:173] op_sel_hi:[1,0] neg_lo:[0,1] neg_hi:[0,1]
	v_max3_f32 v48, v48, v49, v50
	v_max3_f32 v49, v51, v52, v53
	v_max_f32_e32 v50, v82, v83
	v_max_f32_e32 v51, v86, v87
	v_max_f32_e32 v52, v88, v89
	v_max_f32_e32 v53, v90, v91
	v_max3_f32 v54, v92, v93, v54
	v_max3_f32 v50, v80, v81, v50
	v_max3_f32 v51, v84, v85, v51
	v_max3_f32 v52, v52, v53, v54
	v_max3_f32 v50, v50, v51, v52
	v_max3_f32 v48, v48, v49, v50
	ds_bpermute_b32 v49, v218, v48
	s_mov_b32 s8, 0x41000000
	s_waitcnt lgkmcnt(0)
	v_max_f32_e32 v49, v49, v49
	v_max_f32_e32 v48, v48, v49
	v_cmp_lt_f32_e32 vcc, s8, v48
	s_cbranch_vccz .LBB0_1216
	v_max_f32_e32 v48, v48, v48
	v_max_f32_e32 v49, 0, v48
	v_exp_f32_e64 v48, -v49
	v_sub_f32_e32 v96, v96, v49
	v_sub_f32_e32 v97, v97, v49
	v_sub_f32_e32 v98, v98, v49
	v_sub_f32_e32 v99, v99, v49
	v_sub_f32_e32 v100, v100, v49
	v_sub_f32_e32 v101, v101, v49
	v_sub_f32_e32 v102, v102, v49
	v_sub_f32_e32 v103, v103, v49
	v_sub_f32_e32 v104, v104, v49
	v_sub_f32_e32 v105, v105, v49
	v_sub_f32_e32 v106, v106, v49
	v_sub_f32_e32 v107, v107, v49
	v_sub_f32_e32 v108, v108, v49
	v_sub_f32_e32 v109, v109, v49
	v_sub_f32_e32 v110, v110, v49
	v_sub_f32_e32 v111, v111, v49
	v_sub_f32_e32 v80, v80, v49
	v_sub_f32_e32 v81, v81, v49
	v_sub_f32_e32 v82, v82, v49
	v_sub_f32_e32 v83, v83, v49
	v_sub_f32_e32 v84, v84, v49
	v_sub_f32_e32 v85, v85, v49
	v_sub_f32_e32 v86, v86, v49
	v_sub_f32_e32 v87, v87, v49
	v_sub_f32_e32 v88, v88, v49
	v_sub_f32_e32 v89, v89, v49
	v_sub_f32_e32 v90, v90, v49
	v_sub_f32_e32 v91, v91, v49
	v_sub_f32_e32 v92, v92, v49
	v_sub_f32_e32 v93, v93, v49
	v_sub_f32_e32 v94, v94, v49
	v_sub_f32_e32 v95, v95, v49
	v_pk_mul_f32 v[14:15], v[14:15], v[48:49] op_sel_hi:[1,0]
	v_pk_mul_f32 v[12:13], v[12:13], v[48:49] op_sel_hi:[1,0]
	v_pk_mul_f32 v[10:11], v[10:11], v[48:49] op_sel_hi:[1,0]
	v_pk_mul_f32 v[8:9], v[8:9], v[48:49] op_sel_hi:[1,0]
	v_pk_mul_f32 v[6:7], v[6:7], v[48:49] op_sel_hi:[1,0]
	v_pk_mul_f32 v[4:5], v[4:5], v[48:49] op_sel_hi:[1,0]
	v_pk_mul_f32 v[2:3], v[2:3], v[48:49] op_sel_hi:[1,0]
	v_pk_mul_f32 v[0:1], v[0:1], v[48:49] op_sel_hi:[1,0]
	v_pk_mul_f32 v[30:31], v[30:31], v[48:49] op_sel_hi:[1,0]
	v_pk_mul_f32 v[28:29], v[28:29], v[48:49] op_sel_hi:[1,0]
	v_pk_mul_f32 v[26:27], v[26:27], v[48:49] op_sel_hi:[1,0]
	v_pk_mul_f32 v[24:25], v[24:25], v[48:49] op_sel_hi:[1,0]
	v_pk_mul_f32 v[22:23], v[22:23], v[48:49] op_sel_hi:[1,0]
	v_pk_mul_f32 v[20:21], v[20:21], v[48:49] op_sel_hi:[1,0]
	v_pk_mul_f32 v[18:19], v[18:19], v[48:49] op_sel_hi:[1,0]
	v_pk_mul_f32 v[16:17], v[16:17], v[48:49] op_sel_hi:[1,0]
	v_pk_mul_f32 v[46:47], v[46:47], v[48:49] op_sel_hi:[1,0]
	v_pk_mul_f32 v[44:45], v[44:45], v[48:49] op_sel_hi:[1,0]
	v_pk_mul_f32 v[42:43], v[42:43], v[48:49] op_sel_hi:[1,0]
	v_pk_mul_f32 v[40:41], v[40:41], v[48:49] op_sel_hi:[1,0]
	v_pk_mul_f32 v[38:39], v[38:39], v[48:49] op_sel_hi:[1,0]
	v_pk_mul_f32 v[36:37], v[36:37], v[48:49] op_sel_hi:[1,0]
	v_pk_mul_f32 v[34:35], v[34:35], v[48:49] op_sel_hi:[1,0]
	v_pk_mul_f32 v[32:33], v[32:33], v[48:49] op_sel_hi:[1,0]
	v_add_f32_e32 v172, v172, v49
.LBB0_1216:
	ds_read_b128 v[48:51], v199 offset:24576
	ds_read_b128 v[52:55], v199 offset:30720
	ds_read_b128 v[154:157], v200 offset:24576
	ds_read_b128 v[176:179], v200 offset:30720
	ds_read_b128 v[180:183], v199 offset:24640
	ds_read_b128 v[184:187], v199 offset:30784
	ds_read_b128 v[188:191], v200 offset:24640
	ds_read_b128 v[202:205], v200 offset:30784
	ds_read_b128 v[212:215], v199 offset:24704
	ds_read_b128 v[220:223], v199 offset:30848
	ds_read_b128 v[224:227], v200 offset:24704
	ds_read_b128 v[228:231], v200 offset:30848
	s_waitcnt lgkmcnt(0)
	v_mfma_f32_32x32x16_bf16 v[64:79], v[48:51], v[136:139], 0
	v_exp_f32_e32 v150, v96
	v_exp_f32_e32 v151, v97
	v_exp_f32_e32 v152, v80
	v_exp_f32_e32 v153, v81
	v_exp_f32_e32 v167, v82
	v_exp_f32_e32 v169, v83
	v_exp_f32_e32 v201, v109
	v_mfma_f32_32x32x16_bf16 v[48:63], v[52:55], v[136:139], 0
	v_exp_f32_e32 v208, v94
	v_exp_f32_e32 v209, v95
	v_mfma_f32_32x32x16_bf16 v[64:79], v[154:157], v[132:135], v[64:79]
	v_exp_f32_e32 v155, v98
	v_exp_f32_e32 v156, v99
	v_exp_f32_e32 v157, v100
	v_mfma_f32_32x32x16_bf16 v[64:79], v[180:183], v[128:131], v[64:79]
	v_exp_f32_e32 v180, v101
	v_exp_f32_e32 v181, v84
	v_exp_f32_e32 v182, v87
	v_exp_f32_e32 v183, v104
	v_mfma_f32_32x32x16_bf16 v[64:79], v[188:191], v[124:127], v[64:79]
	v_exp_f32_e32 v188, v105
	v_exp_f32_e32 v189, v90
	v_exp_f32_e32 v190, v91
	v_exp_f32_e32 v191, v108
	v_mfma_f32_32x32x16_bf16 v[64:79], v[212:215], v[120:123], v[64:79]
	v_mfma_f32_32x32x16_bf16 v[64:79], v[224:227], v[116:119], v[64:79]
	v_mfma_f32_32x32x16_bf16 v[48:63], v[176:179], v[132:135], v[48:63]
	v_exp_f32_e32 v176, v85
	v_exp_f32_e32 v177, v102
	v_exp_f32_e32 v178, v103
	v_exp_f32_e32 v179, v86
	v_mfma_f32_32x32x16_bf16 v[48:63], v[184:187], v[128:131], v[48:63]
	v_exp_f32_e32 v184, v88
	v_exp_f32_e32 v185, v89
	v_exp_f32_e32 v186, v106
	v_exp_f32_e32 v187, v107
	v_mfma_f32_32x32x16_bf16 v[48:63], v[202:205], v[124:127], v[48:63]
	v_exp_f32_e32 v202, v92
	v_exp_f32_e32 v203, v93
	v_exp_f32_e32 v204, v110
	v_exp_f32_e32 v205, v111
	v_mfma_f32_32x32x16_bf16 v[48:63], v[220:223], v[120:123], v[48:63]
	ds_read_b128 v[80:83], v173 offset:57344
	ds_read_b128 v[84:87], v173 offset:61440
	ds_read_b128 v[88:91], v197 offset:57344
	ds_read_b128 v[92:95], v197 offset:61440
	ds_read_b128 v[96:99], v193 offset:57344
	ds_read_b128 v[100:103], v193 offset:61440
	ds_read_b128 v[104:107], v195 offset:57344
	ds_read_b128 v[108:111], v195 offset:61440
	v_pk_add_f32 v[32:33], v[32:33], v[150:151]
	v_cvt_pk_bf16_f32 v154, v150, v151
	v_add_f32_e32 v34, v34, v155
	v_add_f32_e32 v35, v35, v156
	v_cvt_pk_bf16_f32 v155, v155, v156
	v_add_f32_e32 v32, v32, v157
	v_add_f32_e32 v33, v33, v180
	v_cvt_pk_bf16_f32 v156, v157, v180
	v_add_f32_e32 v34, v34, v177
	v_add_f32_e32 v35, v35, v178
	v_cvt_pk_bf16_f32 v157, v177, v178
	v_mfma_f32_32x32x16_bf16 v[48:63], v[228:231], v[116:119], v[48:63]
	s_cmp_eq_u32 s64, 0
	s_cbranch_scc1 .Lmla_late_skip2
	s_waitcnt vmcnt(0)
	s_barrier
.Lmla_late_skip2:
	s_and_b64 vcc, exec, s[6:7]
	s_waitcnt lgkmcnt(0)
	v_mfma_f32_32x32x16_bf16 v[16:31], v[84:87], v[154:157], v[16:31]
	v_mfma_f32_32x32x16_bf16 v[0:15], v[80:83], v[154:157], v[0:15]
	v_add_f32_e32 v32, v32, v183
	v_add_f32_e32 v33, v33, v188
	v_cvt_pk_bf16_f32 v80, v183, v188
	v_pk_add_f32 v[34:35], v[34:35], v[186:187]
	v_cvt_pk_bf16_f32 v81, v186, v187
	v_add_f32_e32 v32, v32, v191
	v_add_f32_e32 v33, v33, v201
	v_cvt_pk_bf16_f32 v82, v191, v201
	v_cvt_pk_bf16_f32 v83, v204, v205
	v_pk_add_f32 v[34:35], v[34:35], v[204:205]
	s_nop 0
	v_mfma_f32_32x32x16_bf16 v[16:31], v[92:95], v[80:83], v[16:31]
	v_mfma_f32_32x32x16_bf16 v[0:15], v[88:91], v[80:83], v[0:15]
	v_pk_add_f32 v[32:33], v[32:33], v[152:153]
	v_cvt_pk_bf16_f32 v84, v152, v153
	v_add_f32_e32 v34, v34, v167
	v_add_f32_e32 v35, v35, v169
	v_cvt_pk_bf16_f32 v85, v167, v169
	v_add_f32_e32 v32, v32, v181
	v_add_f32_e32 v33, v33, v176
	v_cvt_pk_bf16_f32 v86, v181, v176
	v_cvt_pk_bf16_f32 v87, v179, v182
	v_add_f32_e32 v34, v34, v179
	v_add_f32_e32 v35, v35, v182
	v_mfma_f32_32x32x16_bf16 v[16:31], v[100:103], v[84:87], v[16:31]
	v_mfma_f32_32x32x16_bf16 v[0:15], v[96:99], v[84:87], v[0:15]
	v_pk_add_f32 v[32:33], v[32:33], v[184:185]
	v_cvt_pk_bf16_f32 v80, v184, v185
	v_add_f32_e32 v34, v34, v189
	v_add_f32_e32 v35, v35, v190
	v_cvt_pk_bf16_f32 v81, v189, v190
	v_pk_add_f32 v[32:33], v[32:33], v[202:203]
	v_cvt_pk_bf16_f32 v82, v202, v203
	v_cvt_pk_bf16_f32 v83, v208, v209
	v_pk_add_f32 v[34:35], v[34:35], v[208:209]
	s_nop 0
	v_mfma_f32_32x32x16_bf16 v[16:31], v[108:111], v[80:83], v[16:31]
	v_mfma_f32_32x32x16_bf16 v[0:15], v[104:107], v[80:83], v[0:15]
	s_cbranch_vccnz .LBB0_1219
	v_pk_add_f32 v[70:71], v[70:71], v[172:173] op_sel_hi:[1,0] neg_lo:[0,1] neg_hi:[0,1]
	v_pk_add_f32 v[78:79], v[78:79], v[172:173] op_sel_hi:[1,0] neg_lo:[0,1] neg_hi:[0,1]
	v_pk_add_f32 v[64:65], v[64:65], v[172:173] op_sel_hi:[1,0] neg_lo:[0,1] neg_hi:[0,1]
	v_pk_add_f32 v[66:67], v[66:67], v[172:173] op_sel_hi:[1,0] neg_lo:[0,1] neg_hi:[0,1]
	v_pk_add_f32 v[68:69], v[68:69], v[172:173] op_sel_hi:[1,0] neg_lo:[0,1] neg_hi:[0,1]
	v_pk_add_f32 v[72:73], v[72:73], v[172:173] op_sel_hi:[1,0] neg_lo:[0,1] neg_hi:[0,1]
	v_pk_add_f32 v[74:75], v[74:75], v[172:173] op_sel_hi:[1,0] neg_lo:[0,1] neg_hi:[0,1]
	v_pk_add_f32 v[76:77], v[76:77], v[172:173] op_sel_hi:[1,0] neg_lo:[0,1] neg_hi:[0,1]
	v_pk_add_f32 v[62:63], v[62:63], v[172:173] op_sel_hi:[1,0] neg_lo:[0,1] neg_hi:[0,1]
	v_max_f32_e32 v82, v70, v71
	v_max_f32_e32 v85, v78, v79
	v_pk_add_f32 v[50:51], v[50:51], v[172:173] op_sel_hi:[1,0] neg_lo:[0,1] neg_hi:[0,1]
	v_pk_add_f32 v[54:55], v[54:55], v[172:173] op_sel_hi:[1,0] neg_lo:[0,1] neg_hi:[0,1]
	v_pk_add_f32 v[56:57], v[56:57], v[172:173] op_sel_hi:[1,0] neg_lo:[0,1] neg_hi:[0,1]
	v_pk_add_f32 v[58:59], v[58:59], v[172:173] op_sel_hi:[1,0] neg_lo:[0,1] neg_hi:[0,1]
	v_pk_add_f32 v[60:61], v[60:61], v[172:173] op_sel_hi:[1,0] neg_lo:[0,1] neg_hi:[0,1]
	v_max_f32_e32 v80, v64, v65
	v_max_f32_e32 v81, v66, v67
	v_max3_f32 v82, v68, v69, v82
	v_max_f32_e32 v83, v72, v73
	v_max_f32_e32 v84, v74, v75
	v_max3_f32 v85, v76, v77, v85
	v_max_f32_e32 v86, v62, v63
	v_pk_add_f32 v[48:49], v[48:49], v[172:173] op_sel_hi:[1,0] neg_lo:[0,1] neg_hi:[0,1]
	v_pk_add_f32 v[52:53], v[52:53], v[172:173] op_sel_hi:[1,0] neg_lo:[0,1] neg_hi:[0,1]
	v_max3_f32 v80, v80, v81, v82
	v_max3_f32 v81, v83, v84, v85
	v_max_f32_e32 v82, v50, v51
	v_max_f32_e32 v83, v54, v55
	v_max_f32_e32 v84, v56, v57
	v_max_f32_e32 v85, v58, v59
	v_max3_f32 v86, v60, v61, v86
	v_max3_f32 v82, v48, v49, v82
	v_max3_f32 v83, v52, v53, v83
	v_max3_f32 v84, v84, v85, v86
	v_max3_f32 v82, v82, v83, v84
	v_max3_f32 v80, v80, v81, v82
	ds_bpermute_b32 v81, v218, v80
	s_mov_b32 s8, 0x41000000
	s_waitcnt lgkmcnt(0)
	v_max_f32_e32 v81, v81, v81
	v_max_f32_e32 v80, v80, v81
	v_cmp_lt_f32_e32 vcc, s8, v80
	s_cbranch_vccz .LBB0_1219
	v_max_f32_e32 v80, v80, v80
	v_max_f32_e32 v81, 0, v80
	v_exp_f32_e64 v80, -v81
	v_sub_f32_e32 v64, v64, v81
	v_sub_f32_e32 v65, v65, v81
	v_sub_f32_e32 v66, v66, v81
	v_sub_f32_e32 v67, v67, v81
	v_sub_f32_e32 v68, v68, v81
	v_sub_f32_e32 v69, v69, v81
	v_sub_f32_e32 v70, v70, v81
	v_sub_f32_e32 v71, v71, v81
	v_sub_f32_e32 v72, v72, v81
	v_sub_f32_e32 v73, v73, v81
	v_sub_f32_e32 v74, v74, v81
	v_sub_f32_e32 v75, v75, v81
	v_sub_f32_e32 v76, v76, v81
	v_sub_f32_e32 v77, v77, v81
	v_sub_f32_e32 v78, v78, v81
	v_sub_f32_e32 v79, v79, v81
	v_sub_f32_e32 v48, v48, v81
	v_sub_f32_e32 v49, v49, v81
	v_sub_f32_e32 v50, v50, v81
	v_sub_f32_e32 v51, v51, v81
	v_sub_f32_e32 v52, v52, v81
	v_sub_f32_e32 v53, v53, v81
	v_sub_f32_e32 v54, v54, v81
	v_sub_f32_e32 v55, v55, v81
	v_sub_f32_e32 v56, v56, v81
	v_sub_f32_e32 v57, v57, v81
	v_sub_f32_e32 v58, v58, v81
	v_sub_f32_e32 v59, v59, v81
	v_sub_f32_e32 v60, v60, v81
	v_sub_f32_e32 v61, v61, v81
	v_sub_f32_e32 v62, v62, v81
	v_sub_f32_e32 v63, v63, v81
	v_pk_mul_f32 v[14:15], v[14:15], v[80:81] op_sel_hi:[1,0]
	v_pk_mul_f32 v[12:13], v[12:13], v[80:81] op_sel_hi:[1,0]
	v_pk_mul_f32 v[10:11], v[10:11], v[80:81] op_sel_hi:[1,0]
	v_pk_mul_f32 v[8:9], v[8:9], v[80:81] op_sel_hi:[1,0]
	v_pk_mul_f32 v[6:7], v[6:7], v[80:81] op_sel_hi:[1,0]
	v_pk_mul_f32 v[4:5], v[4:5], v[80:81] op_sel_hi:[1,0]
	v_pk_mul_f32 v[2:3], v[2:3], v[80:81] op_sel_hi:[1,0]
	v_pk_mul_f32 v[0:1], v[0:1], v[80:81] op_sel_hi:[1,0]
	v_pk_mul_f32 v[30:31], v[30:31], v[80:81] op_sel_hi:[1,0]
	v_pk_mul_f32 v[28:29], v[28:29], v[80:81] op_sel_hi:[1,0]
	v_pk_mul_f32 v[26:27], v[26:27], v[80:81] op_sel_hi:[1,0]
	v_pk_mul_f32 v[24:25], v[24:25], v[80:81] op_sel_hi:[1,0]
	v_pk_mul_f32 v[22:23], v[22:23], v[80:81] op_sel_hi:[1,0]
	v_pk_mul_f32 v[20:21], v[20:21], v[80:81] op_sel_hi:[1,0]
	v_pk_mul_f32 v[18:19], v[18:19], v[80:81] op_sel_hi:[1,0]
	v_pk_mul_f32 v[16:17], v[16:17], v[80:81] op_sel_hi:[1,0]
	v_pk_mul_f32 v[46:47], v[46:47], v[80:81] op_sel_hi:[1,0]
	v_pk_mul_f32 v[44:45], v[44:45], v[80:81] op_sel_hi:[1,0]
	v_pk_mul_f32 v[42:43], v[42:43], v[80:81] op_sel_hi:[1,0]
	v_pk_mul_f32 v[40:41], v[40:41], v[80:81] op_sel_hi:[1,0]
	v_pk_mul_f32 v[38:39], v[38:39], v[80:81] op_sel_hi:[1,0]
	v_pk_mul_f32 v[36:37], v[36:37], v[80:81] op_sel_hi:[1,0]
	v_pk_mul_f32 v[34:35], v[34:35], v[80:81] op_sel_hi:[1,0]
	v_pk_mul_f32 v[32:33], v[32:33], v[80:81] op_sel_hi:[1,0]
	v_add_f32_e32 v172, v172, v81

.Lmla_early_skip2:
	s_sub_i32 m0, s60, s66
	s_add_i32 m0, m0, 0x8000
	v_exp_f32_e32 v150, v64
	global_load_lds_dwordx4 v[80:81], off
	ds_read_b128 v[80:83], v199 offset:36864
	ds_read_b128 v[84:87], v199 offset:43008
	ds_read_b128 v[154:157], v200 offset:36864
	ds_read_b128 v[174:177], v200 offset:43008
	ds_read_b128 v[178:181], v199 offset:36928
	ds_read_b128 v[182:185], v199 offset:43072
	ds_read_b128 v[186:189], v200 offset:36928
	ds_read_b128 v[202:205], v200 offset:43072
	ds_read_b128 v[212:215], v199 offset:36992
	ds_read_b128 v[220:223], v199 offset:43136
	ds_read_b128 v[224:227], v200 offset:36992
	ds_read_b128 v[228:231], v200 offset:43136
	s_waitcnt lgkmcnt(0)
	v_mfma_f32_32x32x16_bf16 v[96:111], v[80:83], v[136:139], 0
	v_exp_f32_e32 v151, v65
	v_exp_f32_e32 v152, v48
	v_exp_f32_e32 v153, v49
	v_exp_f32_e32 v167, v50
	v_exp_f32_e32 v169, v51
	v_exp_f32_e32 v190, v77
	v_exp_f32_e32 v191, v60
	v_mfma_f32_32x32x16_bf16 v[80:95], v[84:87], v[136:139], 0
	v_exp_f32_e32 v201, v61
	v_mfma_f32_32x32x16_bf16 v[96:111], v[154:157], v[132:135], v[96:111]
	v_exp_f32_e32 v155, v66
	v_exp_f32_e32 v156, v67
	v_exp_f32_e32 v157, v68
	v_mfma_f32_32x32x16_bf16 v[96:111], v[178:181], v[128:131], v[96:111]
	v_exp_f32_e32 v178, v69
	v_exp_f32_e32 v179, v52
	v_exp_f32_e32 v180, v55
	v_exp_f32_e32 v181, v72
	v_mfma_f32_32x32x16_bf16 v[96:111], v[186:189], v[124:127], v[96:111]
	v_exp_f32_e32 v186, v73
	v_exp_f32_e32 v187, v58
	v_exp_f32_e32 v188, v59
	v_exp_f32_e32 v189, v76
	v_mfma_f32_32x32x16_bf16 v[96:111], v[212:215], v[120:123], v[96:111]
	v_mfma_f32_32x32x16_bf16 v[96:111], v[224:227], v[116:119], v[96:111]
	v_mfma_f32_32x32x16_bf16 v[80:95], v[174:177], v[132:135], v[80:95]
	v_exp_f32_e32 v174, v53
	v_exp_f32_e32 v175, v70
	v_exp_f32_e32 v176, v71
	v_exp_f32_e32 v177, v54
	v_mfma_f32_32x32x16_bf16 v[80:95], v[182:185], v[128:131], v[80:95]
	v_exp_f32_e32 v182, v56
	v_exp_f32_e32 v183, v57
	v_exp_f32_e32 v184, v74
	v_exp_f32_e32 v185, v75
	v_mfma_f32_32x32x16_bf16 v[80:95], v[202:205], v[124:127], v[80:95]
	v_exp_f32_e32 v202, v78
	v_exp_f32_e32 v203, v79
	v_exp_f32_e32 v204, v62
	v_exp_f32_e32 v205, v63
	v_mfma_f32_32x32x16_bf16 v[80:95], v[220:223], v[120:123], v[80:95]
	ds_read_b128 v[48:51], v192 offset:16384
	ds_read_b128 v[52:55], v192 offset:20480
	ds_read_b128 v[56:59], v198 offset:16384
	ds_read_b128 v[60:63], v198 offset:20480
	ds_read_b128 v[64:67], v194 offset:16384
	ds_read_b128 v[68:71], v194 offset:20480
	ds_read_b128 v[72:75], v196 offset:16384
	ds_read_b128 v[76:79], v196 offset:20480
	v_pk_add_f32 v[32:33], v[32:33], v[150:151]
	v_cvt_pk_bf16_f32 v154, v150, v151
	v_add_f32_e32 v34, v34, v155
	v_add_f32_e32 v35, v35, v156
	v_cvt_pk_bf16_f32 v155, v155, v156
	v_add_f32_e32 v32, v32, v157
	v_add_f32_e32 v33, v33, v178
	v_cvt_pk_bf16_f32 v156, v157, v178
	v_add_f32_e32 v34, v34, v175
	v_add_f32_e32 v35, v35, v176
	v_cvt_pk_bf16_f32 v157, v175, v176
	v_mfma_f32_32x32x16_bf16 v[80:95], v[228:231], v[116:119], v[80:95]
	s_and_b64 vcc, exec, s[6:7]
	s_waitcnt lgkmcnt(0)
	v_mfma_f32_32x32x16_bf16 v[16:31], v[52:55], v[154:157], v[16:31]
	v_mfma_f32_32x32x16_bf16 v[0:15], v[48:51], v[154:157], v[0:15]
	v_add_f32_e32 v32, v32, v181
	v_add_f32_e32 v33, v33, v186
	v_cvt_pk_bf16_f32 v48, v181, v186
	v_pk_add_f32 v[34:35], v[34:35], v[184:185]
	v_cvt_pk_bf16_f32 v49, v184, v185
	v_add_f32_e32 v32, v32, v189
	v_add_f32_e32 v33, v33, v190
	v_cvt_pk_bf16_f32 v50, v189, v190
	v_cvt_pk_bf16_f32 v51, v202, v203
	v_pk_add_f32 v[34:35], v[34:35], v[202:203]
	s_nop 0
	v_mfma_f32_32x32x16_bf16 v[16:31], v[60:63], v[48:51], v[16:31]
	v_mfma_f32_32x32x16_bf16 v[0:15], v[56:59], v[48:51], v[0:15]
	v_pk_add_f32 v[32:33], v[32:33], v[152:153]
	v_cvt_pk_bf16_f32 v52, v152, v153
	v_add_f32_e32 v34, v34, v167
	v_add_f32_e32 v35, v35, v169
	v_cvt_pk_bf16_f32 v53, v167, v169
	v_add_f32_e32 v32, v32, v179
	v_add_f32_e32 v33, v33, v174
	v_cvt_pk_bf16_f32 v54, v179, v174
	v_cvt_pk_bf16_f32 v55, v177, v180
	v_add_f32_e32 v34, v34, v177
	v_add_f32_e32 v35, v35, v180
	v_mfma_f32_32x32x16_bf16 v[16:31], v[68:71], v[52:55], v[16:31]
	v_mfma_f32_32x32x16_bf16 v[0:15], v[64:67], v[52:55], v[0:15]
	v_pk_add_f32 v[32:33], v[32:33], v[182:183]
	v_cvt_pk_bf16_f32 v48, v182, v183
	v_add_f32_e32 v34, v34, v187
	v_add_f32_e32 v35, v35, v188
	v_cvt_pk_bf16_f32 v49, v187, v188
	v_add_f32_e32 v32, v32, v191
	v_add_f32_e32 v33, v33, v201
	v_cvt_pk_bf16_f32 v50, v191, v201
	v_cvt_pk_bf16_f32 v51, v204, v205
	v_pk_add_f32 v[34:35], v[34:35], v[204:205]
	s_nop 0
	v_mfma_f32_32x32x16_bf16 v[16:31], v[76:79], v[48:51], v[16:31]
	v_mfma_f32_32x32x16_bf16 v[0:15], v[72:75], v[48:51], v[0:15]
	s_cbranch_vccnz .LBB0_1222
	v_pk_add_f32 v[102:103], v[102:103], v[172:173] op_sel_hi:[1,0] neg_lo:[0,1] neg_hi:[0,1]
	v_pk_add_f32 v[110:111], v[110:111], v[172:173] op_sel_hi:[1,0] neg_lo:[0,1] neg_hi:[0,1]
	v_pk_add_f32 v[96:97], v[96:97], v[172:173] op_sel_hi:[1,0] neg_lo:[0,1] neg_hi:[0,1]
	v_pk_add_f32 v[98:99], v[98:99], v[172:173] op_sel_hi:[1,0] neg_lo:[0,1] neg_hi:[0,1]
	v_pk_add_f32 v[100:101], v[100:101], v[172:173] op_sel_hi:[1,0] neg_lo:[0,1] neg_hi:[0,1]
	v_pk_add_f32 v[104:105], v[104:105], v[172:173] op_sel_hi:[1,0] neg_lo:[0,1] neg_hi:[0,1]
	v_pk_add_f32 v[106:107], v[106:107], v[172:173] op_sel_hi:[1,0] neg_lo:[0,1] neg_hi:[0,1]
	v_pk_add_f32 v[108:109], v[108:109], v[172:173] op_sel_hi:[1,0] neg_lo:[0,1] neg_hi:[0,1]
	v_pk_add_f32 v[94:95], v[94:95], v[172:173] op_sel_hi:[1,0] neg_lo:[0,1] neg_hi:[0,1]
	v_max_f32_e32 v50, v102, v103
	v_max_f32_e32 v53, v110, v111
	v_pk_add_f32 v[82:83], v[82:83], v[172:173] op_sel_hi:[1,0] neg_lo:[0,1] neg_hi:[0,1]
	v_pk_add_f32 v[86:87], v[86:87], v[172:173] op_sel_hi:[1,0] neg_lo:[0,1] neg_hi:[0,1]
	v_pk_add_f32 v[88:89], v[88:89], v[172:173] op_sel_hi:[1,0] neg_lo:[0,1] neg_hi:[0,1]
	v_pk_add_f32 v[90:91], v[90:91], v[172:173] op_sel_hi:[1,0] neg_lo:[0,1] neg_hi:[0,1]
	v_pk_add_f32 v[92:93], v[92:93], v[172:173] op_sel_hi:[1,0] neg_lo:[0,1] neg_hi:[0,1]
	v_max_f32_e32 v48, v96, v97
	v_max_f32_e32 v49, v98, v99
	v_max3_f32 v50, v100, v101, v50
	v_max_f32_e32 v51, v104, v105
	v_max_f32_e32 v52, v106, v107
	v_max3_f32 v53, v108, v109, v53
	v_max_f32_e32 v54, v94, v95
	v_pk_add_f32 v[80:81], v[80:81], v[172:173] op_sel_hi:[1,0] neg_lo:[0,1] neg_hi:[0,1]
	v_pk_add_f32 v[84:85], v[84:85], v[172:173] op_sel_hi:[1,0] neg_lo:[0,1] neg_hi:[0,1]
	v_max3_f32 v48, v48, v49, v50
	v_max3_f32 v49, v51, v52, v53
	v_max_f32_e32 v50, v82, v83
	v_max_f32_e32 v51, v86, v87
	v_max_f32_e32 v52, v88, v89
	v_max_f32_e32 v53, v90, v91
	v_max3_f32 v54, v92, v93, v54
	v_max3_f32 v50, v80, v81, v50
	v_max3_f32 v51, v84, v85, v51
	v_max3_f32 v52, v52, v53, v54
	v_max3_f32 v50, v50, v51, v52
	v_max3_f32 v48, v48, v49, v50
	ds_bpermute_b32 v49, v218, v48
	s_mov_b32 s8, 0x41000000
	s_waitcnt lgkmcnt(0)
	v_max_f32_e32 v49, v49, v49
	v_max_f32_e32 v48, v48, v49
	v_cmp_lt_f32_e32 vcc, s8, v48
	s_cbranch_vccz .LBB0_1222
	v_max_f32_e32 v48, v48, v48
	v_max_f32_e32 v49, 0, v48
	v_exp_f32_e64 v48, -v49
	v_sub_f32_e32 v96, v96, v49
	v_sub_f32_e32 v97, v97, v49
	v_sub_f32_e32 v98, v98, v49
	v_sub_f32_e32 v99, v99, v49
	v_sub_f32_e32 v100, v100, v49
	v_sub_f32_e32 v101, v101, v49
	v_sub_f32_e32 v102, v102, v49
	v_sub_f32_e32 v103, v103, v49
	v_sub_f32_e32 v104, v104, v49
	v_sub_f32_e32 v105, v105, v49
	v_sub_f32_e32 v106, v106, v49
	v_sub_f32_e32 v107, v107, v49
	v_sub_f32_e32 v108, v108, v49
	v_sub_f32_e32 v109, v109, v49
	v_sub_f32_e32 v110, v110, v49
	v_sub_f32_e32 v111, v111, v49
	v_sub_f32_e32 v80, v80, v49
	v_sub_f32_e32 v81, v81, v49
	v_sub_f32_e32 v82, v82, v49
	v_sub_f32_e32 v83, v83, v49
	v_sub_f32_e32 v84, v84, v49
	v_sub_f32_e32 v85, v85, v49
	v_sub_f32_e32 v86, v86, v49
	v_sub_f32_e32 v87, v87, v49
	v_sub_f32_e32 v88, v88, v49
	v_sub_f32_e32 v89, v89, v49
	v_sub_f32_e32 v90, v90, v49
	v_sub_f32_e32 v91, v91, v49
	v_sub_f32_e32 v92, v92, v49
	v_sub_f32_e32 v93, v93, v49
	v_sub_f32_e32 v94, v94, v49
	v_sub_f32_e32 v95, v95, v49
	v_pk_mul_f32 v[14:15], v[14:15], v[48:49] op_sel_hi:[1,0]
	v_pk_mul_f32 v[12:13], v[12:13], v[48:49] op_sel_hi:[1,0]
	v_pk_mul_f32 v[10:11], v[10:11], v[48:49] op_sel_hi:[1,0]
	v_pk_mul_f32 v[8:9], v[8:9], v[48:49] op_sel_hi:[1,0]
	v_pk_mul_f32 v[6:7], v[6:7], v[48:49] op_sel_hi:[1,0]
	v_pk_mul_f32 v[4:5], v[4:5], v[48:49] op_sel_hi:[1,0]
	v_pk_mul_f32 v[2:3], v[2:3], v[48:49] op_sel_hi:[1,0]
	v_pk_mul_f32 v[0:1], v[0:1], v[48:49] op_sel_hi:[1,0]
	v_pk_mul_f32 v[30:31], v[30:31], v[48:49] op_sel_hi:[1,0]
	v_pk_mul_f32 v[28:29], v[28:29], v[48:49] op_sel_hi:[1,0]
	v_pk_mul_f32 v[26:27], v[26:27], v[48:49] op_sel_hi:[1,0]
	v_pk_mul_f32 v[24:25], v[24:25], v[48:49] op_sel_hi:[1,0]
	v_pk_mul_f32 v[22:23], v[22:23], v[48:49] op_sel_hi:[1,0]
	v_pk_mul_f32 v[20:21], v[20:21], v[48:49] op_sel_hi:[1,0]
	v_pk_mul_f32 v[18:19], v[18:19], v[48:49] op_sel_hi:[1,0]
	v_pk_mul_f32 v[16:17], v[16:17], v[48:49] op_sel_hi:[1,0]
	v_pk_mul_f32 v[46:47], v[46:47], v[48:49] op_sel_hi:[1,0]
	v_pk_mul_f32 v[44:45], v[44:45], v[48:49] op_sel_hi:[1,0]
	v_pk_mul_f32 v[42:43], v[42:43], v[48:49] op_sel_hi:[1,0]
	v_pk_mul_f32 v[40:41], v[40:41], v[48:49] op_sel_hi:[1,0]
	v_pk_mul_f32 v[38:39], v[38:39], v[48:49] op_sel_hi:[1,0]
	v_pk_mul_f32 v[36:37], v[36:37], v[48:49] op_sel_hi:[1,0]
	v_pk_mul_f32 v[34:35], v[34:35], v[48:49] op_sel_hi:[1,0]
	v_pk_mul_f32 v[32:33], v[32:33], v[48:49] op_sel_hi:[1,0]
	v_add_f32_e32 v172, v172, v49
.LBB0_1222:
	ds_read_b128 v[48:51], v199
	ds_read_b128 v[64:67], v200
	ds_read_b128 v[68:71], v199 offset:64
	ds_read_b128 v[72:75], v200 offset:64
	ds_read_b128 v[76:79], v199 offset:128
	ds_read_b128 v[154:157], v200 offset:128
	v_exp_f32_e32 v96, v96
	v_exp_f32_e32 v97, v97
	v_exp_f32_e32 v98, v98
	s_waitcnt lgkmcnt(0)
	v_mfma_f32_32x32x16_bf16 v[48:63], v[48:51], v[136:139], 0
	v_exp_f32_e32 v136, v80
	v_exp_f32_e32 v137, v81
	v_exp_f32_e32 v99, v99
	v_exp_f32_e32 v100, v100
	v_exp_f32_e32 v101, v101
	v_exp_f32_e32 v102, v102
	v_exp_f32_e32 v103, v103
	v_mfma_f32_32x32x16_bf16 v[48:63], v[64:67], v[132:135], v[48:63]
	v_exp_f32_e32 v132, v82
	v_exp_f32_e32 v133, v83
	v_exp_f32_e32 v134, v84
	v_exp_f32_e32 v104, v104
	v_exp_f32_e32 v105, v105
	v_exp_f32_e32 v106, v106
	v_exp_f32_e32 v107, v107
	v_mfma_f32_32x32x16_bf16 v[48:63], v[68:71], v[128:131], v[48:63]
	v_exp_f32_e32 v128, v85
	v_exp_f32_e32 v129, v86
	v_exp_f32_e32 v130, v87
	v_exp_f32_e32 v108, v108
	v_exp_f32_e32 v109, v109
	v_exp_f32_e32 v92, v92
	v_exp_f32_e32 v93, v93
	v_mfma_f32_32x32x16_bf16 v[48:63], v[72:75], v[124:127], v[48:63]
	v_exp_f32_e32 v124, v88
	v_exp_f32_e32 v125, v89
	v_exp_f32_e32 v126, v90
	v_exp_f32_e32 v127, v91
	v_exp_f32_e32 v110, v110
	v_exp_f32_e32 v111, v111
	v_exp_f32_e32 v94, v94
	v_mfma_f32_32x32x16_bf16 v[48:63], v[76:79], v[120:123], v[48:63]
	v_exp_f32_e32 v95, v95
	v_mfma_f32_32x32x16_bf16 v[48:63], v[154:157], v[116:119], v[48:63]
	s_nop 11
	ds_read_b128 v[56:59], v192 offset:24576
	ds_read_b128 v[60:63], v192 offset:28672
	ds_read_b128 v[64:67], v198 offset:24576
	ds_read_b128 v[68:71], v198 offset:28672
	ds_read_b128 v[72:75], v194 offset:24576
	ds_read_b128 v[76:79], v194 offset:28672
	ds_read_b128 v[80:83], v196 offset:24576
	ds_read_b128 v[84:87], v196 offset:28672
	v_pk_add_f32 v[32:33], v[32:33], v[96:97]
	v_cvt_pk_bf16_f32 v88, v96, v97
	v_pk_add_f32 v[34:35], v[34:35], v[98:99]
	v_cvt_pk_bf16_f32 v89, v98, v99
	v_pk_add_f32 v[32:33], v[32:33], v[100:101]
	v_cvt_pk_bf16_f32 v90, v100, v101
	v_pk_add_f32 v[34:35], v[34:35], v[102:103]
	v_cvt_pk_bf16_f32 v91, v102, v103
	s_cmp_eq_u32 s64, 0
	s_cbranch_scc1 .Lmla_late_skip3
	s_waitcnt vmcnt(0)
	s_barrier
.Lmla_late_skip3:
	s_and_b64 vcc, exec, s[6:7]
	s_waitcnt lgkmcnt(0)
	v_mfma_f32_32x32x16_bf16 v[16:31], v[60:63], v[88:91], v[16:31]
	v_mfma_f32_32x32x16_bf16 v[0:15], v[56:59], v[88:91], v[0:15]
	v_pk_add_f32 v[32:33], v[32:33], v[104:105]
	v_cvt_pk_bf16_f32 v56, v104, v105
	v_pk_add_f32 v[34:35], v[34:35], v[106:107]
	v_cvt_pk_bf16_f32 v57, v106, v107
	v_pk_add_f32 v[32:33], v[32:33], v[108:109]
	v_cvt_pk_bf16_f32 v58, v108, v109
	v_pk_add_f32 v[34:35], v[34:35], v[110:111]
	v_cvt_pk_bf16_f32 v59, v110, v111
	s_nop 1
	v_mfma_f32_32x32x16_bf16 v[16:31], v[68:71], v[56:59], v[16:31]
	v_mfma_f32_32x32x16_bf16 v[0:15], v[64:67], v[56:59], v[0:15]
	v_pk_add_f32 v[32:33], v[32:33], v[136:137]
	v_cvt_pk_bf16_f32 v56, v136, v137
	v_pk_add_f32 v[34:35], v[34:35], v[132:133]
	v_cvt_pk_bf16_f32 v57, v132, v133
	v_add_f32_e32 v32, v32, v134
	v_add_f32_e32 v33, v33, v128
	v_cvt_pk_bf16_f32 v58, v134, v128
	v_add_f32_e32 v34, v34, v129
	v_add_f32_e32 v35, v35, v130
	v_cvt_pk_bf16_f32 v59, v129, v130
	s_nop 1
	v_mfma_f32_32x32x16_bf16 v[16:31], v[76:79], v[56:59], v[16:31]
	v_mfma_f32_32x32x16_bf16 v[0:15], v[72:75], v[56:59], v[0:15]
	v_pk_add_f32 v[32:33], v[32:33], v[124:125]
	v_cvt_pk_bf16_f32 v56, v124, v125
	v_pk_add_f32 v[34:35], v[34:35], v[126:127]
	v_cvt_pk_bf16_f32 v57, v126, v127
	v_pk_add_f32 v[32:33], v[32:33], v[92:93]
	v_cvt_pk_bf16_f32 v58, v92, v93
	v_pk_add_f32 v[34:35], v[34:35], v[94:95]
	v_cvt_pk_bf16_f32 v59, v94, v95
	s_nop 1
	v_mfma_f32_32x32x16_bf16 v[16:31], v[84:87], v[56:59], v[16:31]
	v_mfma_f32_32x32x16_bf16 v[0:15], v[80:83], v[56:59], v[0:15]
	s_cbranch_vccnz .LBB0_1176
	v_pk_add_f32 v[50:51], v[50:51], v[172:173] op_sel_hi:[1,0] neg_lo:[0,1] neg_hi:[0,1]
	v_pk_add_f32 v[54:55], v[54:55], v[172:173] op_sel_hi:[1,0] neg_lo:[0,1] neg_hi:[0,1]
	v_pk_add_f32 v[48:49], v[48:49], v[172:173] op_sel_hi:[1,0] neg_lo:[0,1] neg_hi:[0,1]
	v_pk_add_f32 v[52:53], v[52:53], v[172:173] op_sel_hi:[1,0] neg_lo:[0,1] neg_hi:[0,1]
	v_max_f32_e32 v57, v50, v51
	v_max_f32_e32 v58, v54, v55
	v_sub_f32_e32 v56, 0xff800000, v172
	v_max3_f32 v57, v48, v49, v57
	v_max3_f32 v58, v52, v53, v58
	v_max3_f32 v57, v57, v58, v56
	ds_bpermute_b32 v58, v218, v57
	s_mov_b32 s6, 0x41000000
	s_waitcnt lgkmcnt(0)
	v_max_f32_e32 v58, v58, v58
	v_max_f32_e32 v57, v57, v58
	v_cmp_lt_f32_e32 vcc, s6, v57
	s_cbranch_vccz .LBB0_1177
	v_max_f32_e32 v57, v57, v57
	v_max_f32_e32 v58, 0, v57
	v_exp_f32_e64 v60, -v58
	v_sub_f32_e32 v56, v56, v58
	v_pk_add_f32 v[48:49], v[48:49], v[58:59] op_sel_hi:[1,0] neg_lo:[0,1] neg_hi:[0,1]
	v_pk_add_f32 v[50:51], v[50:51], v[58:59] op_sel_hi:[1,0] neg_lo:[0,1] neg_hi:[0,1]
	v_pk_add_f32 v[52:53], v[52:53], v[58:59] op_sel_hi:[1,0] neg_lo:[0,1] neg_hi:[0,1]
	v_pk_add_f32 v[54:55], v[54:55], v[58:59] op_sel_hi:[1,0] neg_lo:[0,1] neg_hi:[0,1]
	v_pk_mul_f32 v[14:15], v[14:15], v[60:61] op_sel_hi:[1,0]
	v_pk_mul_f32 v[12:13], v[12:13], v[60:61] op_sel_hi:[1,0]
	v_pk_mul_f32 v[10:11], v[10:11], v[60:61] op_sel_hi:[1,0]
	v_pk_mul_f32 v[8:9], v[8:9], v[60:61] op_sel_hi:[1,0]
	v_pk_mul_f32 v[6:7], v[6:7], v[60:61] op_sel_hi:[1,0]
	v_pk_mul_f32 v[4:5], v[4:5], v[60:61] op_sel_hi:[1,0]
	v_pk_mul_f32 v[2:3], v[2:3], v[60:61] op_sel_hi:[1,0]
	v_pk_mul_f32 v[0:1], v[0:1], v[60:61] op_sel_hi:[1,0]
	v_pk_mul_f32 v[30:31], v[30:31], v[60:61] op_sel_hi:[1,0]
	v_pk_mul_f32 v[28:29], v[28:29], v[60:61] op_sel_hi:[1,0]
	v_pk_mul_f32 v[26:27], v[26:27], v[60:61] op_sel_hi:[1,0]
	v_pk_mul_f32 v[24:25], v[24:25], v[60:61] op_sel_hi:[1,0]
	v_pk_mul_f32 v[22:23], v[22:23], v[60:61] op_sel_hi:[1,0]
	v_pk_mul_f32 v[20:21], v[20:21], v[60:61] op_sel_hi:[1,0]
	v_pk_mul_f32 v[18:19], v[18:19], v[60:61] op_sel_hi:[1,0]
	v_pk_mul_f32 v[16:17], v[16:17], v[60:61] op_sel_hi:[1,0]
	v_pk_mul_f32 v[46:47], v[46:47], v[60:61] op_sel_hi:[1,0]
	v_pk_mul_f32 v[44:45], v[44:45], v[60:61] op_sel_hi:[1,0]
	v_pk_mul_f32 v[42:43], v[42:43], v[60:61] op_sel_hi:[1,0]
	v_pk_mul_f32 v[40:41], v[40:41], v[60:61] op_sel_hi:[1,0]
	v_pk_mul_f32 v[38:39], v[38:39], v[60:61] op_sel_hi:[1,0]
	v_pk_mul_f32 v[36:37], v[36:37], v[60:61] op_sel_hi:[1,0]
	v_pk_mul_f32 v[34:35], v[34:35], v[60:61] op_sel_hi:[1,0]
	v_pk_mul_f32 v[32:33], v[32:33], v[60:61] op_sel_hi:[1,0]
	s_branch .LBB0_1177
